# MFMA order variant: n outer across merged 32-MFMA segment, then bj, m, k innermost (adjacent same-accumulator pairs)
# speedup vs baseline: 1.0179x; 1.0002x over previous
.LBB0_177:
	ds_read_b128 v[164:167], v153
	ds_read_b128 v[168:171], v153 offset:1024
	ds_read_b128 v[172:175], v153 offset:2048
	ds_read_b128 v[176:179], v153 offset:3072
	ds_read_b128 v[184:187], v160
	ds_read_b128 v[188:191], v160 offset:1024
	ds_read_b128 v[192:195], v160 offset:2048
	ds_read_b128 v[196:199], v160 offset:3072
	s_add_u32 s28, s26, 0xfff00080
	s_addc_u32 s29, s27, -1
	s_cmp_eq_u32 s80, 60
	s_cselect_b32 s31, s19, s29
	s_cselect_b32 s30, s58, s28
	s_cselect_b32 s29, s17, s63
	s_cselect_b32 s28, s59, s62
	v_lshl_add_u64 v[148:149], s[26:27], 0, v[140:141]
	s_add_i32 m0, s25, 0xc000
	ds_read_b128 v[200:203], v161
	ds_read_b128 v[204:207], v161 offset:1024
	ds_read_b128 v[208:211], v161 offset:2048
	ds_read_b128 v[212:215], v161 offset:3072
	ds_read_b128 v[216:219], v161 offset:4096
	ds_read_b128 v[220:223], v161 offset:5120
	ds_read_b128 v[224:227], v161 offset:6144
	ds_read_b128 v[228:231], v161 offset:7168
	global_load_lds_dwordx4 v[148:149], off
	v_lshl_add_u64 v[148:149], s[26:27], 0, v[142:143]
	s_add_i32 m0, s25, 0xe000
	s_nop 0
	global_load_lds_dwordx4 v[148:149], off
	s_waitcnt vmcnt(8)
	s_waitcnt lgkmcnt(0)
	s_barrier
	s_waitcnt lgkmcnt(0)
	v_mfma_f32_16x16x32_bf16 v[126:129], v[164:167], v[200:203], v[126:129]
	v_mfma_f32_16x16x32_bf16 v[126:129], v[168:171], v[204:207], v[126:129]
	v_mfma_f32_16x16x32_bf16 v[118:121], v[164:167], v[208:211], v[118:121]
	v_mfma_f32_16x16x32_bf16 v[118:121], v[168:171], v[212:215], v[118:121]
	v_mfma_f32_16x16x32_bf16 v[102:105], v[164:167], v[216:219], v[102:105]
	v_mfma_f32_16x16x32_bf16 v[102:105], v[168:171], v[220:223], v[102:105]
	v_mfma_f32_16x16x32_bf16 v[86:89], v[164:167], v[224:227], v[86:89]
	v_mfma_f32_16x16x32_bf16 v[86:89], v[168:171], v[228:231], v[86:89]
	v_mfma_f32_16x16x32_bf16 v[114:117], v[184:187], v[200:203], v[114:117]
	v_mfma_f32_16x16x32_bf16 v[114:117], v[188:191], v[204:207], v[114:117]
	v_mfma_f32_16x16x32_bf16 v[98:101], v[184:187], v[208:211], v[98:101]
	v_mfma_f32_16x16x32_bf16 v[98:101], v[188:191], v[212:215], v[98:101]
	v_mfma_f32_16x16x32_bf16 v[82:85], v[184:187], v[216:219], v[82:85]
	v_mfma_f32_16x16x32_bf16 v[82:85], v[188:191], v[220:223], v[82:85]
	v_mfma_f32_16x16x32_bf16 v[70:73], v[184:187], v[224:227], v[70:73]
	v_mfma_f32_16x16x32_bf16 v[70:73], v[188:191], v[228:231], v[70:73]
	v_mfma_f32_16x16x32_bf16 v[122:125], v[172:175], v[200:203], v[122:125]
	v_mfma_f32_16x16x32_bf16 v[122:125], v[176:179], v[204:207], v[122:125]
	v_mfma_f32_16x16x32_bf16 v[110:113], v[172:175], v[208:211], v[110:113]
	v_mfma_f32_16x16x32_bf16 v[110:113], v[176:179], v[212:215], v[110:113]
	v_mfma_f32_16x16x32_bf16 v[94:97], v[172:175], v[216:219], v[94:97]
	v_mfma_f32_16x16x32_bf16 v[94:97], v[176:179], v[220:223], v[94:97]
	v_mfma_f32_16x16x32_bf16 v[78:81], v[172:175], v[224:227], v[78:81]
	v_mfma_f32_16x16x32_bf16 v[78:81], v[176:179], v[228:231], v[78:81]
	v_mfma_f32_16x16x32_bf16 v[106:109], v[192:195], v[200:203], v[106:109]
	v_mfma_f32_16x16x32_bf16 v[106:109], v[196:199], v[204:207], v[106:109]
	v_mfma_f32_16x16x32_bf16 v[90:93], v[192:195], v[208:211], v[90:93]
	v_mfma_f32_16x16x32_bf16 v[90:93], v[196:199], v[212:215], v[90:93]
	v_mfma_f32_16x16x32_bf16 v[74:77], v[192:195], v[216:219], v[74:77]
	v_mfma_f32_16x16x32_bf16 v[74:77], v[196:199], v[220:223], v[74:77]
	v_mfma_f32_16x16x32_bf16 v[66:69], v[192:195], v[224:227], v[66:69]
	v_mfma_f32_16x16x32_bf16 v[66:69], v[196:199], v[228:231], v[66:69]
	s_barrier
	s_add_i32 s81, s51, s34
	v_lshl_add_u64 v[148:149], s[28:29], 0, v[132:133]
	s_mov_b32 m0, s81
	ds_read_b128 v[200:203], v161 offset:16384
	ds_read_b128 v[204:207], v161 offset:17408
	ds_read_b128 v[208:211], v161 offset:18432
	ds_read_b128 v[212:215], v161 offset:19456
	ds_read_b128 v[216:219], v161 offset:20480
	ds_read_b128 v[220:223], v161 offset:21504
	ds_read_b128 v[224:227], v161 offset:22528
	ds_read_b128 v[228:231], v161 offset:23552
	global_load_lds_dwordx4 v[148:149], off
	s_add_i32 m0, s81, 0x2000
	s_add_u32 s82, s28, 0x100000
	v_lshl_add_u64 v[180:181], s[28:29], 0, v[136:137]
	s_addc_u32 s83, s29, 0
	s_add_i32 s81, s52, s34
	global_load_lds_dwordx4 v[180:181], off
	v_lshl_add_u64 v[232:233], s[82:83], 0, v[132:133]
	s_mov_b32 m0, s81
	v_lshl_add_u64 v[234:235], s[30:31], 0, v[134:135]
	global_load_lds_dwordx4 v[232:233], off
	v_lshl_add_u64 v[232:233], s[82:83], 0, v[136:137]
	s_add_i32 m0, s81, 0x2000
	s_nop 0
	global_load_lds_dwordx4 v[232:233], off
	v_lshl_add_u64 v[232:233], s[30:31], 0, v[130:131]
	s_mov_b32 m0, s25
	s_nop 0
	global_load_lds_dwordx4 v[232:233], off
	s_mov_b32 m0, s43
	s_nop 0
	global_load_lds_dwordx4 v[234:235], off
	s_waitcnt vmcnt(8)
	s_waitcnt lgkmcnt(0)
	s_barrier
	s_waitcnt lgkmcnt(0)
	v_mfma_f32_16x16x32_bf16 v[62:65], v[164:167], v[200:203], v[62:65]
	v_mfma_f32_16x16x32_bf16 v[62:65], v[168:171], v[204:207], v[62:65]
	v_mfma_f32_16x16x32_bf16 v[54:57], v[164:167], v[208:211], v[54:57]
	v_mfma_f32_16x16x32_bf16 v[54:57], v[168:171], v[212:215], v[54:57]
	v_mfma_f32_16x16x32_bf16 v[38:41], v[164:167], v[216:219], v[38:41]
	v_mfma_f32_16x16x32_bf16 v[38:41], v[168:171], v[220:223], v[38:41]
	v_mfma_f32_16x16x32_bf16 v[22:25], v[164:167], v[224:227], v[22:25]
	v_mfma_f32_16x16x32_bf16 v[22:25], v[168:171], v[228:231], v[22:25]
	v_mfma_f32_16x16x32_bf16 v[50:53], v[184:187], v[200:203], v[50:53]
	v_mfma_f32_16x16x32_bf16 v[50:53], v[188:191], v[204:207], v[50:53]
	v_mfma_f32_16x16x32_bf16 v[34:37], v[184:187], v[208:211], v[34:37]
	v_mfma_f32_16x16x32_bf16 v[34:37], v[188:191], v[212:215], v[34:37]
	v_mfma_f32_16x16x32_bf16 v[18:21], v[184:187], v[216:219], v[18:21]
	v_mfma_f32_16x16x32_bf16 v[18:21], v[188:191], v[220:223], v[18:21]
	v_mfma_f32_16x16x32_bf16 v[6:9], v[184:187], v[224:227], v[6:9]
	v_mfma_f32_16x16x32_bf16 v[6:9], v[188:191], v[228:231], v[6:9]
	v_mfma_f32_16x16x32_bf16 v[58:61], v[172:175], v[200:203], v[58:61]
	v_mfma_f32_16x16x32_bf16 v[58:61], v[176:179], v[204:207], v[58:61]
	v_mfma_f32_16x16x32_bf16 v[46:49], v[172:175], v[208:211], v[46:49]
	v_mfma_f32_16x16x32_bf16 v[46:49], v[176:179], v[212:215], v[46:49]
	v_mfma_f32_16x16x32_bf16 v[30:33], v[172:175], v[216:219], v[30:33]
	v_mfma_f32_16x16x32_bf16 v[30:33], v[176:179], v[220:223], v[30:33]
	v_mfma_f32_16x16x32_bf16 v[14:17], v[172:175], v[224:227], v[14:17]
	v_mfma_f32_16x16x32_bf16 v[14:17], v[176:179], v[228:231], v[14:17]
	v_mfma_f32_16x16x32_bf16 v[42:45], v[192:195], v[200:203], v[42:45]
	v_mfma_f32_16x16x32_bf16 v[42:45], v[196:199], v[204:207], v[42:45]
	v_mfma_f32_16x16x32_bf16 v[26:29], v[192:195], v[208:211], v[26:29]
	v_mfma_f32_16x16x32_bf16 v[26:29], v[196:199], v[212:215], v[26:29]
	v_mfma_f32_16x16x32_bf16 v[10:13], v[192:195], v[216:219], v[10:13]
	v_mfma_f32_16x16x32_bf16 v[10:13], v[196:199], v[220:223], v[10:13]
	v_mfma_f32_16x16x32_bf16 v[2:5], v[192:195], v[224:227], v[2:5]
	v_mfma_f32_16x16x32_bf16 v[2:5], v[196:199], v[228:231], v[2:5]
	s_barrier
	s_add_i32 s81, 0, 0x18000
	v_add_u32_e32 v162, s81, v151
	s_add_i32 s82, 0, 0x1c000
	ds_read_b128 v[164:167], v162
	ds_read_b128 v[168:171], v162 offset:1024
	ds_read_b128 v[172:175], v162 offset:2048
	ds_read_b128 v[176:179], v162 offset:3072
	v_add_u32_e32 v162, s82, v151
	ds_read_b128 v[184:187], v162
	ds_read_b128 v[188:191], v162 offset:1024
	ds_read_b128 v[192:195], v162 offset:2048
	ds_read_b128 v[196:199], v162 offset:3072
	s_add_u32 s30, s30, 0x100000
	s_addc_u32 s31, s31, 0
	s_mov_b32 m0, s44
	v_lshl_add_u64 v[236:237], s[30:31], 0, v[130:131]
	ds_read_b128 v[200:203], v161 offset:32768
	ds_read_b128 v[204:207], v161 offset:33792
	ds_read_b128 v[208:211], v161 offset:34816
	ds_read_b128 v[212:215], v161 offset:35840
	ds_read_b128 v[216:219], v161 offset:36864
	ds_read_b128 v[220:223], v161 offset:37888
	ds_read_b128 v[224:227], v161 offset:38912
	ds_read_b128 v[228:231], v161 offset:39936
	global_load_lds_dwordx4 v[236:237], off
	v_lshl_add_u64 v[236:237], s[30:31], 0, v[134:135]
	s_mov_b32 m0, s45
	s_nop 0
	global_load_lds_dwordx4 v[236:237], off
	s_waitcnt vmcnt(8)
	s_waitcnt lgkmcnt(0)
	s_barrier
	s_waitcnt lgkmcnt(0)
	v_mfma_f32_16x16x32_bf16 v[126:129], v[164:167], v[200:203], v[126:129]
	v_mfma_f32_16x16x32_bf16 v[126:129], v[168:171], v[204:207], v[126:129]
	v_mfma_f32_16x16x32_bf16 v[118:121], v[164:167], v[208:211], v[118:121]
	v_mfma_f32_16x16x32_bf16 v[118:121], v[168:171], v[212:215], v[118:121]
	v_mfma_f32_16x16x32_bf16 v[102:105], v[164:167], v[216:219], v[102:105]
	v_mfma_f32_16x16x32_bf16 v[102:105], v[168:171], v[220:223], v[102:105]
	v_mfma_f32_16x16x32_bf16 v[86:89], v[164:167], v[224:227], v[86:89]
	v_mfma_f32_16x16x32_bf16 v[86:89], v[168:171], v[228:231], v[86:89]
	v_mfma_f32_16x16x32_bf16 v[114:117], v[184:187], v[200:203], v[114:117]
	v_mfma_f32_16x16x32_bf16 v[114:117], v[188:191], v[204:207], v[114:117]
	v_mfma_f32_16x16x32_bf16 v[98:101], v[184:187], v[208:211], v[98:101]
	v_mfma_f32_16x16x32_bf16 v[98:101], v[188:191], v[212:215], v[98:101]
	v_mfma_f32_16x16x32_bf16 v[82:85], v[184:187], v[216:219], v[82:85]
	v_mfma_f32_16x16x32_bf16 v[82:85], v[188:191], v[220:223], v[82:85]
	v_mfma_f32_16x16x32_bf16 v[70:73], v[184:187], v[224:227], v[70:73]
	v_mfma_f32_16x16x32_bf16 v[70:73], v[188:191], v[228:231], v[70:73]
	v_mfma_f32_16x16x32_bf16 v[122:125], v[172:175], v[200:203], v[122:125]
	v_mfma_f32_16x16x32_bf16 v[122:125], v[176:179], v[204:207], v[122:125]
	v_mfma_f32_16x16x32_bf16 v[110:113], v[172:175], v[208:211], v[110:113]
	v_mfma_f32_16x16x32_bf16 v[110:113], v[176:179], v[212:215], v[110:113]
	v_mfma_f32_16x16x32_bf16 v[94:97], v[172:175], v[216:219], v[94:97]
	v_mfma_f32_16x16x32_bf16 v[94:97], v[176:179], v[220:223], v[94:97]
	v_mfma_f32_16x16x32_bf16 v[78:81], v[172:175], v[224:227], v[78:81]
	v_mfma_f32_16x16x32_bf16 v[78:81], v[176:179], v[228:231], v[78:81]
	v_mfma_f32_16x16x32_bf16 v[106:109], v[192:195], v[200:203], v[106:109]
	v_mfma_f32_16x16x32_bf16 v[106:109], v[196:199], v[204:207], v[106:109]
	v_mfma_f32_16x16x32_bf16 v[90:93], v[192:195], v[208:211], v[90:93]
	v_mfma_f32_16x16x32_bf16 v[90:93], v[196:199], v[212:215], v[90:93]
	v_mfma_f32_16x16x32_bf16 v[74:77], v[192:195], v[216:219], v[74:77]
	v_mfma_f32_16x16x32_bf16 v[74:77], v[196:199], v[220:223], v[74:77]
	v_mfma_f32_16x16x32_bf16 v[66:69], v[192:195], v[224:227], v[66:69]
	v_mfma_f32_16x16x32_bf16 v[66:69], v[196:199], v[228:231], v[66:69]
	s_barrier
	s_add_i32 s30, s81, s34
	v_lshl_add_u64 v[148:149], v[148:149], 0, s[12:13]
	s_mov_b32 m0, s30
	ds_read_b128 v[200:203], v161 offset:49152
	ds_read_b128 v[204:207], v161 offset:50176
	ds_read_b128 v[208:211], v161 offset:51200
	ds_read_b128 v[212:215], v161 offset:52224
	ds_read_b128 v[216:219], v161 offset:53248
	ds_read_b128 v[220:223], v161 offset:54272
	ds_read_b128 v[224:227], v161 offset:55296
	ds_read_b128 v[228:231], v161 offset:56320
	global_load_lds_dwordx4 v[148:149], off
	s_add_i32 m0, s30, 0x2000
	s_add_u32 s28, s28, 0x100080
	v_lshl_add_u64 v[148:149], v[180:181], 0, s[12:13]
	s_addc_u32 s29, s29, 0
	s_add_i32 s30, s82, s34
	global_load_lds_dwordx4 v[148:149], off
	v_lshl_add_u64 v[148:149], s[28:29], 0, v[132:133]
	s_mov_b32 m0, s30
	s_nop 0
	global_load_lds_dwordx4 v[148:149], off
	v_lshl_add_u64 v[148:149], s[28:29], 0, v[136:137]
	s_add_i32 m0, s30, 0x2000
	s_nop 0
	global_load_lds_dwordx4 v[148:149], off
	v_lshl_add_u64 v[148:149], v[232:233], 0, s[12:13]
	s_mov_b32 m0, s46
	s_nop 0
	global_load_lds_dwordx4 v[148:149], off
	v_lshl_add_u64 v[148:149], v[234:235], 0, s[12:13]
	s_mov_b32 m0, s47
	s_nop 0
	global_load_lds_dwordx4 v[148:149], off
	s_waitcnt vmcnt(8)
	s_waitcnt lgkmcnt(0)
	s_barrier
	s_waitcnt lgkmcnt(0)
	v_mfma_f32_16x16x32_bf16 v[62:65], v[164:167], v[200:203], v[62:65]
	v_mfma_f32_16x16x32_bf16 v[62:65], v[168:171], v[204:207], v[62:65]
	v_mfma_f32_16x16x32_bf16 v[54:57], v[164:167], v[208:211], v[54:57]
	v_mfma_f32_16x16x32_bf16 v[54:57], v[168:171], v[212:215], v[54:57]
	v_mfma_f32_16x16x32_bf16 v[38:41], v[164:167], v[216:219], v[38:41]
	v_mfma_f32_16x16x32_bf16 v[38:41], v[168:171], v[220:223], v[38:41]
	v_mfma_f32_16x16x32_bf16 v[22:25], v[164:167], v[224:227], v[22:25]
	v_mfma_f32_16x16x32_bf16 v[22:25], v[168:171], v[228:231], v[22:25]
	v_mfma_f32_16x16x32_bf16 v[50:53], v[184:187], v[200:203], v[50:53]
	v_mfma_f32_16x16x32_bf16 v[50:53], v[188:191], v[204:207], v[50:53]
	v_mfma_f32_16x16x32_bf16 v[34:37], v[184:187], v[208:211], v[34:37]
	v_mfma_f32_16x16x32_bf16 v[34:37], v[188:191], v[212:215], v[34:37]
	v_mfma_f32_16x16x32_bf16 v[18:21], v[184:187], v[216:219], v[18:21]
	v_mfma_f32_16x16x32_bf16 v[18:21], v[188:191], v[220:223], v[18:21]
	v_mfma_f32_16x16x32_bf16 v[6:9], v[184:187], v[224:227], v[6:9]
	v_mfma_f32_16x16x32_bf16 v[6:9], v[188:191], v[228:231], v[6:9]
	v_mfma_f32_16x16x32_bf16 v[58:61], v[172:175], v[200:203], v[58:61]
	v_mfma_f32_16x16x32_bf16 v[58:61], v[176:179], v[204:207], v[58:61]
	v_mfma_f32_16x16x32_bf16 v[46:49], v[172:175], v[208:211], v[46:49]
	v_mfma_f32_16x16x32_bf16 v[46:49], v[176:179], v[212:215], v[46:49]
	v_mfma_f32_16x16x32_bf16 v[30:33], v[172:175], v[216:219], v[30:33]
	v_mfma_f32_16x16x32_bf16 v[30:33], v[176:179], v[220:223], v[30:33]
	v_mfma_f32_16x16x32_bf16 v[14:17], v[172:175], v[224:227], v[14:17]
	v_mfma_f32_16x16x32_bf16 v[14:17], v[176:179], v[228:231], v[14:17]
	v_mfma_f32_16x16x32_bf16 v[42:45], v[192:195], v[200:203], v[42:45]
	v_mfma_f32_16x16x32_bf16 v[42:45], v[196:199], v[204:207], v[42:45]
	v_mfma_f32_16x16x32_bf16 v[26:29], v[192:195], v[208:211], v[26:29]
	v_mfma_f32_16x16x32_bf16 v[26:29], v[196:199], v[212:215], v[26:29]
	v_mfma_f32_16x16x32_bf16 v[10:13], v[192:195], v[216:219], v[10:13]
	v_mfma_f32_16x16x32_bf16 v[10:13], v[196:199], v[220:223], v[10:13]
	v_mfma_f32_16x16x32_bf16 v[2:5], v[192:195], v[224:227], v[2:5]
	v_mfma_f32_16x16x32_bf16 v[2:5], v[196:199], v[228:231], v[2:5]
	s_barrier
	s_add_i32 s80, s80, 2
	s_add_u32 s26, s26, 0x100
	s_addc_u32 s27, s27, 0
	s_add_u32 s62, s62, 0x100
	s_addc_u32 s63, s63, 0
	s_cmp_gt_u32 s80, 61
	s_cbranch_scc0 .LBB0_177
	s_and_b64 vcc, exec, s[14:15]
	s_cbranch_vccz .LBB0_180
	s_barrier

.LBB0_197:
	ds_read_b128 v[164:167], v153
	ds_read_b128 v[168:171], v153 offset:1024
	ds_read_b128 v[172:175], v153 offset:2048
	ds_read_b128 v[176:179], v153 offset:3072
	ds_read_b128 v[184:187], v160
	ds_read_b128 v[188:191], v160 offset:1024
	ds_read_b128 v[192:195], v160 offset:2048
	ds_read_b128 v[196:199], v160 offset:3072
	s_add_u32 s30, s28, 0xfff00080
	s_addc_u32 s31, s29, -1
	s_cmp_eq_u32 s83, 60
	s_cselect_b32 s35, s21, s31
	s_cselect_b32 s34, s63, s30
	s_cselect_b32 s31, s19, s82
	s_cselect_b32 s30, s80, s81
	v_lshl_add_u64 v[148:149], s[28:29], 0, v[140:141]
	s_add_i32 m0, s27, 0xc000
	ds_read_b128 v[200:203], v161
	ds_read_b128 v[204:207], v161 offset:1024
	ds_read_b128 v[208:211], v161 offset:2048
	ds_read_b128 v[212:215], v161 offset:3072
	ds_read_b128 v[216:219], v161 offset:4096
	ds_read_b128 v[220:223], v161 offset:5120
	ds_read_b128 v[224:227], v161 offset:6144
	ds_read_b128 v[228:231], v161 offset:7168
	global_load_lds_dwordx4 v[148:149], off
	v_lshl_add_u64 v[148:149], s[28:29], 0, v[142:143]
	s_add_i32 m0, s27, 0xe000
	s_nop 0
	global_load_lds_dwordx4 v[148:149], off
	s_waitcnt vmcnt(8)
	s_waitcnt lgkmcnt(0)
	s_barrier
	s_waitcnt lgkmcnt(0)
	v_mfma_f32_16x16x32_bf16 v[126:129], v[164:167], v[200:203], v[126:129]
	v_mfma_f32_16x16x32_bf16 v[126:129], v[168:171], v[204:207], v[126:129]
	v_mfma_f32_16x16x32_bf16 v[110:113], v[164:167], v[208:211], v[110:113]
	v_mfma_f32_16x16x32_bf16 v[110:113], v[168:171], v[212:215], v[110:113]
	v_mfma_f32_16x16x32_bf16 v[94:97], v[164:167], v[216:219], v[94:97]
	v_mfma_f32_16x16x32_bf16 v[94:97], v[168:171], v[220:223], v[94:97]
	v_mfma_f32_16x16x32_bf16 v[78:81], v[164:167], v[224:227], v[78:81]
	v_mfma_f32_16x16x32_bf16 v[78:81], v[168:171], v[228:231], v[78:81]
	v_mfma_f32_16x16x32_bf16 v[118:121], v[184:187], v[200:203], v[118:121]
	v_mfma_f32_16x16x32_bf16 v[118:121], v[188:191], v[204:207], v[118:121]
	v_mfma_f32_16x16x32_bf16 v[102:105], v[184:187], v[208:211], v[102:105]
	v_mfma_f32_16x16x32_bf16 v[102:105], v[188:191], v[212:215], v[102:105]
	v_mfma_f32_16x16x32_bf16 v[86:89], v[184:187], v[216:219], v[86:89]
	v_mfma_f32_16x16x32_bf16 v[86:89], v[188:191], v[220:223], v[86:89]
	v_mfma_f32_16x16x32_bf16 v[70:73], v[184:187], v[224:227], v[70:73]
	v_mfma_f32_16x16x32_bf16 v[70:73], v[188:191], v[228:231], v[70:73]
	v_mfma_f32_16x16x32_bf16 v[122:125], v[172:175], v[200:203], v[122:125]
	v_mfma_f32_16x16x32_bf16 v[122:125], v[176:179], v[204:207], v[122:125]
	v_mfma_f32_16x16x32_bf16 v[106:109], v[172:175], v[208:211], v[106:109]
	v_mfma_f32_16x16x32_bf16 v[106:109], v[176:179], v[212:215], v[106:109]
	v_mfma_f32_16x16x32_bf16 v[90:93], v[172:175], v[216:219], v[90:93]
	v_mfma_f32_16x16x32_bf16 v[90:93], v[176:179], v[220:223], v[90:93]
	v_mfma_f32_16x16x32_bf16 v[74:77], v[172:175], v[224:227], v[74:77]
	v_mfma_f32_16x16x32_bf16 v[74:77], v[176:179], v[228:231], v[74:77]
	v_mfma_f32_16x16x32_bf16 v[114:117], v[192:195], v[200:203], v[114:117]
	v_mfma_f32_16x16x32_bf16 v[114:117], v[196:199], v[204:207], v[114:117]
	v_mfma_f32_16x16x32_bf16 v[98:101], v[192:195], v[208:211], v[98:101]
	v_mfma_f32_16x16x32_bf16 v[98:101], v[196:199], v[212:215], v[98:101]
	v_mfma_f32_16x16x32_bf16 v[82:85], v[192:195], v[216:219], v[82:85]
	v_mfma_f32_16x16x32_bf16 v[82:85], v[196:199], v[220:223], v[82:85]
	v_mfma_f32_16x16x32_bf16 v[66:69], v[192:195], v[224:227], v[66:69]
	v_mfma_f32_16x16x32_bf16 v[66:69], v[196:199], v[228:231], v[66:69]
	s_barrier
	s_add_i32 s84, s58, s43
	v_lshl_add_u64 v[148:149], s[30:31], 0, v[132:133]
	s_mov_b32 m0, s84
	ds_read_b128 v[200:203], v161 offset:16384
	ds_read_b128 v[204:207], v161 offset:17408
	ds_read_b128 v[208:211], v161 offset:18432
	ds_read_b128 v[212:215], v161 offset:19456
	ds_read_b128 v[216:219], v161 offset:20480
	ds_read_b128 v[220:223], v161 offset:21504
	ds_read_b128 v[224:227], v161 offset:22528
	ds_read_b128 v[228:231], v161 offset:23552
	global_load_lds_dwordx4 v[148:149], off
	s_add_i32 m0, s84, 0x2000
	s_add_u32 s84, s30, 0x100000
	v_lshl_add_u64 v[180:181], s[30:31], 0, v[136:137]
	s_addc_u32 s85, s31, 0
	s_add_i32 s86, s59, s43
	global_load_lds_dwordx4 v[180:181], off
	v_lshl_add_u64 v[232:233], s[84:85], 0, v[132:133]
	s_mov_b32 m0, s86
	v_lshl_add_u64 v[234:235], s[34:35], 0, v[134:135]
	global_load_lds_dwordx4 v[232:233], off
	v_lshl_add_u64 v[232:233], s[84:85], 0, v[136:137]
	s_add_i32 m0, s86, 0x2000
	s_nop 0
	global_load_lds_dwordx4 v[232:233], off
	v_lshl_add_u64 v[232:233], s[34:35], 0, v[130:131]
	s_mov_b32 m0, s27
	s_nop 0
	global_load_lds_dwordx4 v[232:233], off
	s_mov_b32 m0, s46
	s_nop 0
	global_load_lds_dwordx4 v[234:235], off
	s_waitcnt vmcnt(8)
	s_waitcnt lgkmcnt(0)
	s_barrier
	s_waitcnt lgkmcnt(0)
	v_mfma_f32_16x16x32_bf16 v[62:65], v[164:167], v[200:203], v[62:65]
	v_mfma_f32_16x16x32_bf16 v[62:65], v[168:171], v[204:207], v[62:65]
	v_mfma_f32_16x16x32_bf16 v[46:49], v[164:167], v[208:211], v[46:49]
	v_mfma_f32_16x16x32_bf16 v[46:49], v[168:171], v[212:215], v[46:49]
	v_mfma_f32_16x16x32_bf16 v[30:33], v[164:167], v[216:219], v[30:33]
	v_mfma_f32_16x16x32_bf16 v[30:33], v[168:171], v[220:223], v[30:33]
	v_mfma_f32_16x16x32_bf16 v[14:17], v[164:167], v[224:227], v[14:17]
	v_mfma_f32_16x16x32_bf16 v[14:17], v[168:171], v[228:231], v[14:17]
	v_mfma_f32_16x16x32_bf16 v[54:57], v[184:187], v[200:203], v[54:57]
	v_mfma_f32_16x16x32_bf16 v[54:57], v[188:191], v[204:207], v[54:57]
	v_mfma_f32_16x16x32_bf16 v[38:41], v[184:187], v[208:211], v[38:41]
	v_mfma_f32_16x16x32_bf16 v[38:41], v[188:191], v[212:215], v[38:41]
	v_mfma_f32_16x16x32_bf16 v[22:25], v[184:187], v[216:219], v[22:25]
	v_mfma_f32_16x16x32_bf16 v[22:25], v[188:191], v[220:223], v[22:25]
	v_mfma_f32_16x16x32_bf16 v[6:9], v[184:187], v[224:227], v[6:9]
	v_mfma_f32_16x16x32_bf16 v[6:9], v[188:191], v[228:231], v[6:9]
	v_mfma_f32_16x16x32_bf16 v[58:61], v[172:175], v[200:203], v[58:61]
	v_mfma_f32_16x16x32_bf16 v[58:61], v[176:179], v[204:207], v[58:61]
	v_mfma_f32_16x16x32_bf16 v[42:45], v[172:175], v[208:211], v[42:45]
	v_mfma_f32_16x16x32_bf16 v[42:45], v[176:179], v[212:215], v[42:45]
	v_mfma_f32_16x16x32_bf16 v[26:29], v[172:175], v[216:219], v[26:29]
	v_mfma_f32_16x16x32_bf16 v[26:29], v[176:179], v[220:223], v[26:29]
	v_mfma_f32_16x16x32_bf16 v[10:13], v[172:175], v[224:227], v[10:13]
	v_mfma_f32_16x16x32_bf16 v[10:13], v[176:179], v[228:231], v[10:13]
	v_mfma_f32_16x16x32_bf16 v[50:53], v[192:195], v[200:203], v[50:53]
	v_mfma_f32_16x16x32_bf16 v[50:53], v[196:199], v[204:207], v[50:53]
	v_mfma_f32_16x16x32_bf16 v[34:37], v[192:195], v[208:211], v[34:37]
	v_mfma_f32_16x16x32_bf16 v[34:37], v[196:199], v[212:215], v[34:37]
	v_mfma_f32_16x16x32_bf16 v[18:21], v[192:195], v[216:219], v[18:21]
	v_mfma_f32_16x16x32_bf16 v[18:21], v[196:199], v[220:223], v[18:21]
	v_mfma_f32_16x16x32_bf16 v[2:5], v[192:195], v[224:227], v[2:5]
	v_mfma_f32_16x16x32_bf16 v[2:5], v[196:199], v[228:231], v[2:5]
	s_barrier
	s_add_i32 s84, 0, 0x18000
	v_add_u32_e32 v162, s84, v151
	s_add_i32 s85, 0, 0x1c000
	ds_read_b128 v[164:167], v162
	ds_read_b128 v[168:171], v162 offset:1024
	ds_read_b128 v[172:175], v162 offset:2048
	ds_read_b128 v[176:179], v162 offset:3072
	v_add_u32_e32 v162, s85, v151
	ds_read_b128 v[184:187], v162
	ds_read_b128 v[188:191], v162 offset:1024
	ds_read_b128 v[192:195], v162 offset:2048
	ds_read_b128 v[196:199], v162 offset:3072
	s_add_u32 s34, s34, 0x100000
	s_addc_u32 s35, s35, 0
	s_mov_b32 m0, s47
	v_lshl_add_u64 v[236:237], s[34:35], 0, v[130:131]
	ds_read_b128 v[200:203], v161 offset:32768
	ds_read_b128 v[204:207], v161 offset:33792
	ds_read_b128 v[208:211], v161 offset:34816
	ds_read_b128 v[212:215], v161 offset:35840
	ds_read_b128 v[216:219], v161 offset:36864
	ds_read_b128 v[220:223], v161 offset:37888
	ds_read_b128 v[224:227], v161 offset:38912
	ds_read_b128 v[228:231], v161 offset:39936
	global_load_lds_dwordx4 v[236:237], off
	v_lshl_add_u64 v[236:237], s[34:35], 0, v[134:135]
	s_mov_b32 m0, s50
	s_nop 0
	global_load_lds_dwordx4 v[236:237], off
	s_waitcnt vmcnt(8)
	s_waitcnt lgkmcnt(0)
	s_barrier
	s_waitcnt lgkmcnt(0)
	v_mfma_f32_16x16x32_bf16 v[126:129], v[164:167], v[200:203], v[126:129]
	v_mfma_f32_16x16x32_bf16 v[126:129], v[168:171], v[204:207], v[126:129]
	v_mfma_f32_16x16x32_bf16 v[110:113], v[164:167], v[208:211], v[110:113]
	v_mfma_f32_16x16x32_bf16 v[110:113], v[168:171], v[212:215], v[110:113]
	v_mfma_f32_16x16x32_bf16 v[94:97], v[164:167], v[216:219], v[94:97]
	v_mfma_f32_16x16x32_bf16 v[94:97], v[168:171], v[220:223], v[94:97]
	v_mfma_f32_16x16x32_bf16 v[78:81], v[164:167], v[224:227], v[78:81]
	v_mfma_f32_16x16x32_bf16 v[78:81], v[168:171], v[228:231], v[78:81]
	v_mfma_f32_16x16x32_bf16 v[118:121], v[184:187], v[200:203], v[118:121]
	v_mfma_f32_16x16x32_bf16 v[118:121], v[188:191], v[204:207], v[118:121]
	v_mfma_f32_16x16x32_bf16 v[102:105], v[184:187], v[208:211], v[102:105]
	v_mfma_f32_16x16x32_bf16 v[102:105], v[188:191], v[212:215], v[102:105]
	v_mfma_f32_16x16x32_bf16 v[86:89], v[184:187], v[216:219], v[86:89]
	v_mfma_f32_16x16x32_bf16 v[86:89], v[188:191], v[220:223], v[86:89]
	v_mfma_f32_16x16x32_bf16 v[70:73], v[184:187], v[224:227], v[70:73]
	v_mfma_f32_16x16x32_bf16 v[70:73], v[188:191], v[228:231], v[70:73]
	v_mfma_f32_16x16x32_bf16 v[122:125], v[172:175], v[200:203], v[122:125]
	v_mfma_f32_16x16x32_bf16 v[122:125], v[176:179], v[204:207], v[122:125]
	v_mfma_f32_16x16x32_bf16 v[106:109], v[172:175], v[208:211], v[106:109]
	v_mfma_f32_16x16x32_bf16 v[106:109], v[176:179], v[212:215], v[106:109]
	v_mfma_f32_16x16x32_bf16 v[90:93], v[172:175], v[216:219], v[90:93]
	v_mfma_f32_16x16x32_bf16 v[90:93], v[176:179], v[220:223], v[90:93]
	v_mfma_f32_16x16x32_bf16 v[74:77], v[172:175], v[224:227], v[74:77]
	v_mfma_f32_16x16x32_bf16 v[74:77], v[176:179], v[228:231], v[74:77]
	v_mfma_f32_16x16x32_bf16 v[114:117], v[192:195], v[200:203], v[114:117]
	v_mfma_f32_16x16x32_bf16 v[114:117], v[196:199], v[204:207], v[114:117]
	v_mfma_f32_16x16x32_bf16 v[98:101], v[192:195], v[208:211], v[98:101]
	v_mfma_f32_16x16x32_bf16 v[98:101], v[196:199], v[212:215], v[98:101]
	v_mfma_f32_16x16x32_bf16 v[82:85], v[192:195], v[216:219], v[82:85]
	v_mfma_f32_16x16x32_bf16 v[82:85], v[196:199], v[220:223], v[82:85]
	v_mfma_f32_16x16x32_bf16 v[66:69], v[192:195], v[224:227], v[66:69]
	v_mfma_f32_16x16x32_bf16 v[66:69], v[196:199], v[228:231], v[66:69]
	s_barrier
	s_add_i32 s34, s84, s43
	v_lshl_add_u64 v[148:149], v[148:149], 0, s[14:15]
	s_mov_b32 m0, s34
	ds_read_b128 v[200:203], v161 offset:49152
	ds_read_b128 v[204:207], v161 offset:50176
	ds_read_b128 v[208:211], v161 offset:51200
	ds_read_b128 v[212:215], v161 offset:52224
	ds_read_b128 v[216:219], v161 offset:53248
	ds_read_b128 v[220:223], v161 offset:54272
	ds_read_b128 v[224:227], v161 offset:55296
	ds_read_b128 v[228:231], v161 offset:56320
	global_load_lds_dwordx4 v[148:149], off
	s_add_i32 m0, s34, 0x2000
	s_add_u32 s30, s30, 0x100080
	v_lshl_add_u64 v[148:149], v[180:181], 0, s[14:15]
	s_addc_u32 s31, s31, 0
	s_add_i32 s34, s85, s43
	global_load_lds_dwordx4 v[148:149], off
	v_lshl_add_u64 v[148:149], s[30:31], 0, v[132:133]
	s_mov_b32 m0, s34
	s_nop 0
	global_load_lds_dwordx4 v[148:149], off
	v_lshl_add_u64 v[148:149], s[30:31], 0, v[136:137]
	s_add_i32 m0, s34, 0x2000
	s_nop 0
	global_load_lds_dwordx4 v[148:149], off
	v_lshl_add_u64 v[148:149], v[232:233], 0, s[14:15]
	s_mov_b32 m0, s52
	s_nop 0
	global_load_lds_dwordx4 v[148:149], off
	v_lshl_add_u64 v[148:149], v[234:235], 0, s[14:15]
	s_mov_b32 m0, s53
	s_nop 0
	global_load_lds_dwordx4 v[148:149], off
	s_waitcnt vmcnt(8)
	s_waitcnt lgkmcnt(0)
	s_barrier
	s_waitcnt lgkmcnt(0)
	v_mfma_f32_16x16x32_bf16 v[62:65], v[164:167], v[200:203], v[62:65]
	v_mfma_f32_16x16x32_bf16 v[62:65], v[168:171], v[204:207], v[62:65]
	v_mfma_f32_16x16x32_bf16 v[46:49], v[164:167], v[208:211], v[46:49]
	v_mfma_f32_16x16x32_bf16 v[46:49], v[168:171], v[212:215], v[46:49]
	v_mfma_f32_16x16x32_bf16 v[30:33], v[164:167], v[216:219], v[30:33]
	v_mfma_f32_16x16x32_bf16 v[30:33], v[168:171], v[220:223], v[30:33]
	v_mfma_f32_16x16x32_bf16 v[14:17], v[164:167], v[224:227], v[14:17]
	v_mfma_f32_16x16x32_bf16 v[14:17], v[168:171], v[228:231], v[14:17]
	v_mfma_f32_16x16x32_bf16 v[54:57], v[184:187], v[200:203], v[54:57]
	v_mfma_f32_16x16x32_bf16 v[54:57], v[188:191], v[204:207], v[54:57]
	v_mfma_f32_16x16x32_bf16 v[38:41], v[184:187], v[208:211], v[38:41]
	v_mfma_f32_16x16x32_bf16 v[38:41], v[188:191], v[212:215], v[38:41]
	v_mfma_f32_16x16x32_bf16 v[22:25], v[184:187], v[216:219], v[22:25]
	v_mfma_f32_16x16x32_bf16 v[22:25], v[188:191], v[220:223], v[22:25]
	v_mfma_f32_16x16x32_bf16 v[6:9], v[184:187], v[224:227], v[6:9]
	v_mfma_f32_16x16x32_bf16 v[6:9], v[188:191], v[228:231], v[6:9]
	v_mfma_f32_16x16x32_bf16 v[58:61], v[172:175], v[200:203], v[58:61]
	v_mfma_f32_16x16x32_bf16 v[58:61], v[176:179], v[204:207], v[58:61]
	v_mfma_f32_16x16x32_bf16 v[42:45], v[172:175], v[208:211], v[42:45]
	v_mfma_f32_16x16x32_bf16 v[42:45], v[176:179], v[212:215], v[42:45]
	v_mfma_f32_16x16x32_bf16 v[26:29], v[172:175], v[216:219], v[26:29]
	v_mfma_f32_16x16x32_bf16 v[26:29], v[176:179], v[220:223], v[26:29]
	v_mfma_f32_16x16x32_bf16 v[10:13], v[172:175], v[224:227], v[10:13]
	v_mfma_f32_16x16x32_bf16 v[10:13], v[176:179], v[228:231], v[10:13]
	v_mfma_f32_16x16x32_bf16 v[50:53], v[192:195], v[200:203], v[50:53]
	v_mfma_f32_16x16x32_bf16 v[50:53], v[196:199], v[204:207], v[50:53]
	v_mfma_f32_16x16x32_bf16 v[34:37], v[192:195], v[208:211], v[34:37]
	v_mfma_f32_16x16x32_bf16 v[34:37], v[196:199], v[212:215], v[34:37]
	v_mfma_f32_16x16x32_bf16 v[18:21], v[192:195], v[216:219], v[18:21]
	v_mfma_f32_16x16x32_bf16 v[18:21], v[196:199], v[220:223], v[18:21]
	v_mfma_f32_16x16x32_bf16 v[2:5], v[192:195], v[224:227], v[2:5]
	v_mfma_f32_16x16x32_bf16 v[2:5], v[196:199], v[228:231], v[2:5]
	s_barrier
	s_add_i32 s83, s83, 2
	s_add_u32 s28, s28, 0x100
	s_addc_u32 s29, s29, 0
	s_add_u32 s81, s81, 0x100
	s_addc_u32 s82, s82, 0
	s_cmp_gt_u32 s83, 61
	s_cbranch_scc0 .LBB0_197
	s_and_b64 vcc, exec, s[16:17]
	s_cbranch_vccz .LBB0_200
	s_barrier

.LBB0_217:
	ds_read_b128 v[164:167], v153
	ds_read_b128 v[168:171], v153 offset:1024
	ds_read_b128 v[172:175], v153 offset:2048
	ds_read_b128 v[176:179], v153 offset:3072
	ds_read_b128 v[184:187], v160
	ds_read_b128 v[188:191], v160 offset:1024
	ds_read_b128 v[192:195], v160 offset:2048
	ds_read_b128 v[196:199], v160 offset:3072
	s_add_u32 s30, s28, 0xfff00080
	s_addc_u32 s31, s29, -1
	s_cmp_eq_u32 s83, 60
	s_cselect_b32 s35, s21, s31
	s_cselect_b32 s34, s63, s30
	s_cselect_b32 s31, s19, s82
	s_cselect_b32 s30, s80, s81
	v_lshl_add_u64 v[148:149], s[28:29], 0, v[140:141]
	s_add_i32 m0, s27, 0xc000
	ds_read_b128 v[200:203], v161
	ds_read_b128 v[204:207], v161 offset:1024
	ds_read_b128 v[208:211], v161 offset:2048
	ds_read_b128 v[212:215], v161 offset:3072
	ds_read_b128 v[216:219], v161 offset:4096
	ds_read_b128 v[220:223], v161 offset:5120
	ds_read_b128 v[224:227], v161 offset:6144
	ds_read_b128 v[228:231], v161 offset:7168
	global_load_lds_dwordx4 v[148:149], off
	v_lshl_add_u64 v[148:149], s[28:29], 0, v[142:143]
	s_add_i32 m0, s27, 0xe000
	s_nop 0
	global_load_lds_dwordx4 v[148:149], off
	s_waitcnt vmcnt(8)
	s_waitcnt lgkmcnt(0)
	s_barrier
	s_waitcnt lgkmcnt(0)
	v_mfma_f32_16x16x32_bf16 v[126:129], v[164:167], v[200:203], v[126:129]
	v_mfma_f32_16x16x32_bf16 v[126:129], v[168:171], v[204:207], v[126:129]
	v_mfma_f32_16x16x32_bf16 v[118:121], v[164:167], v[208:211], v[118:121]
	v_mfma_f32_16x16x32_bf16 v[118:121], v[168:171], v[212:215], v[118:121]
	v_mfma_f32_16x16x32_bf16 v[102:105], v[164:167], v[216:219], v[102:105]
	v_mfma_f32_16x16x32_bf16 v[102:105], v[168:171], v[220:223], v[102:105]
	v_mfma_f32_16x16x32_bf16 v[86:89], v[164:167], v[224:227], v[86:89]
	v_mfma_f32_16x16x32_bf16 v[86:89], v[168:171], v[228:231], v[86:89]
	v_mfma_f32_16x16x32_bf16 v[114:117], v[184:187], v[200:203], v[114:117]
	v_mfma_f32_16x16x32_bf16 v[114:117], v[188:191], v[204:207], v[114:117]
	v_mfma_f32_16x16x32_bf16 v[98:101], v[184:187], v[208:211], v[98:101]
	v_mfma_f32_16x16x32_bf16 v[98:101], v[188:191], v[212:215], v[98:101]
	v_mfma_f32_16x16x32_bf16 v[82:85], v[184:187], v[216:219], v[82:85]
	v_mfma_f32_16x16x32_bf16 v[82:85], v[188:191], v[220:223], v[82:85]
	v_mfma_f32_16x16x32_bf16 v[70:73], v[184:187], v[224:227], v[70:73]
	v_mfma_f32_16x16x32_bf16 v[70:73], v[188:191], v[228:231], v[70:73]
	v_mfma_f32_16x16x32_bf16 v[122:125], v[172:175], v[200:203], v[122:125]
	v_mfma_f32_16x16x32_bf16 v[122:125], v[176:179], v[204:207], v[122:125]
	v_mfma_f32_16x16x32_bf16 v[110:113], v[172:175], v[208:211], v[110:113]
	v_mfma_f32_16x16x32_bf16 v[110:113], v[176:179], v[212:215], v[110:113]
	v_mfma_f32_16x16x32_bf16 v[94:97], v[172:175], v[216:219], v[94:97]
	v_mfma_f32_16x16x32_bf16 v[94:97], v[176:179], v[220:223], v[94:97]
	v_mfma_f32_16x16x32_bf16 v[78:81], v[172:175], v[224:227], v[78:81]
	v_mfma_f32_16x16x32_bf16 v[78:81], v[176:179], v[228:231], v[78:81]
	v_mfma_f32_16x16x32_bf16 v[106:109], v[192:195], v[200:203], v[106:109]
	v_mfma_f32_16x16x32_bf16 v[106:109], v[196:199], v[204:207], v[106:109]
	v_mfma_f32_16x16x32_bf16 v[90:93], v[192:195], v[208:211], v[90:93]
	v_mfma_f32_16x16x32_bf16 v[90:93], v[196:199], v[212:215], v[90:93]
	v_mfma_f32_16x16x32_bf16 v[74:77], v[192:195], v[216:219], v[74:77]
	v_mfma_f32_16x16x32_bf16 v[74:77], v[196:199], v[220:223], v[74:77]
	v_mfma_f32_16x16x32_bf16 v[66:69], v[192:195], v[224:227], v[66:69]
	v_mfma_f32_16x16x32_bf16 v[66:69], v[196:199], v[228:231], v[66:69]
	s_barrier
	s_add_i32 s84, s58, s43
	v_lshl_add_u64 v[148:149], s[30:31], 0, v[132:133]
	s_mov_b32 m0, s84
	ds_read_b128 v[200:203], v161 offset:16384
	ds_read_b128 v[204:207], v161 offset:17408
	ds_read_b128 v[208:211], v161 offset:18432
	ds_read_b128 v[212:215], v161 offset:19456
	ds_read_b128 v[216:219], v161 offset:20480
	ds_read_b128 v[220:223], v161 offset:21504
	ds_read_b128 v[224:227], v161 offset:22528
	ds_read_b128 v[228:231], v161 offset:23552
	global_load_lds_dwordx4 v[148:149], off
	s_add_i32 m0, s84, 0x2000
	s_add_u32 s84, s30, 0x100000
	v_lshl_add_u64 v[180:181], s[30:31], 0, v[136:137]
	s_addc_u32 s85, s31, 0
	s_add_i32 s86, s59, s43
	global_load_lds_dwordx4 v[180:181], off
	v_lshl_add_u64 v[232:233], s[84:85], 0, v[132:133]
	s_mov_b32 m0, s86
	v_lshl_add_u64 v[234:235], s[34:35], 0, v[134:135]
	global_load_lds_dwordx4 v[232:233], off
	v_lshl_add_u64 v[232:233], s[84:85], 0, v[136:137]
	s_add_i32 m0, s86, 0x2000
	s_nop 0
	global_load_lds_dwordx4 v[232:233], off
	v_lshl_add_u64 v[232:233], s[34:35], 0, v[130:131]
	s_mov_b32 m0, s27
	s_nop 0
	global_load_lds_dwordx4 v[232:233], off
	s_mov_b32 m0, s46
	s_nop 0
	global_load_lds_dwordx4 v[234:235], off
	s_waitcnt vmcnt(8)
	s_waitcnt lgkmcnt(0)
	s_barrier
	s_waitcnt lgkmcnt(0)
	v_mfma_f32_16x16x32_bf16 v[62:65], v[164:167], v[200:203], v[62:65]
	v_mfma_f32_16x16x32_bf16 v[62:65], v[168:171], v[204:207], v[62:65]
	v_mfma_f32_16x16x32_bf16 v[54:57], v[164:167], v[208:211], v[54:57]
	v_mfma_f32_16x16x32_bf16 v[54:57], v[168:171], v[212:215], v[54:57]
	v_mfma_f32_16x16x32_bf16 v[38:41], v[164:167], v[216:219], v[38:41]
	v_mfma_f32_16x16x32_bf16 v[38:41], v[168:171], v[220:223], v[38:41]
	v_mfma_f32_16x16x32_bf16 v[22:25], v[164:167], v[224:227], v[22:25]
	v_mfma_f32_16x16x32_bf16 v[22:25], v[168:171], v[228:231], v[22:25]
	v_mfma_f32_16x16x32_bf16 v[50:53], v[184:187], v[200:203], v[50:53]
	v_mfma_f32_16x16x32_bf16 v[50:53], v[188:191], v[204:207], v[50:53]
	v_mfma_f32_16x16x32_bf16 v[34:37], v[184:187], v[208:211], v[34:37]
	v_mfma_f32_16x16x32_bf16 v[34:37], v[188:191], v[212:215], v[34:37]
	v_mfma_f32_16x16x32_bf16 v[18:21], v[184:187], v[216:219], v[18:21]
	v_mfma_f32_16x16x32_bf16 v[18:21], v[188:191], v[220:223], v[18:21]
	v_mfma_f32_16x16x32_bf16 v[6:9], v[184:187], v[224:227], v[6:9]
	v_mfma_f32_16x16x32_bf16 v[6:9], v[188:191], v[228:231], v[6:9]
	v_mfma_f32_16x16x32_bf16 v[58:61], v[172:175], v[200:203], v[58:61]
	v_mfma_f32_16x16x32_bf16 v[58:61], v[176:179], v[204:207], v[58:61]
	v_mfma_f32_16x16x32_bf16 v[46:49], v[172:175], v[208:211], v[46:49]
	v_mfma_f32_16x16x32_bf16 v[46:49], v[176:179], v[212:215], v[46:49]
	v_mfma_f32_16x16x32_bf16 v[30:33], v[172:175], v[216:219], v[30:33]
	v_mfma_f32_16x16x32_bf16 v[30:33], v[176:179], v[220:223], v[30:33]
	v_mfma_f32_16x16x32_bf16 v[14:17], v[172:175], v[224:227], v[14:17]
	v_mfma_f32_16x16x32_bf16 v[14:17], v[176:179], v[228:231], v[14:17]
	v_mfma_f32_16x16x32_bf16 v[42:45], v[192:195], v[200:203], v[42:45]
	v_mfma_f32_16x16x32_bf16 v[42:45], v[196:199], v[204:207], v[42:45]
	v_mfma_f32_16x16x32_bf16 v[26:29], v[192:195], v[208:211], v[26:29]
	v_mfma_f32_16x16x32_bf16 v[26:29], v[196:199], v[212:215], v[26:29]
	v_mfma_f32_16x16x32_bf16 v[10:13], v[192:195], v[216:219], v[10:13]
	v_mfma_f32_16x16x32_bf16 v[10:13], v[196:199], v[220:223], v[10:13]
	v_mfma_f32_16x16x32_bf16 v[2:5], v[192:195], v[224:227], v[2:5]
	v_mfma_f32_16x16x32_bf16 v[2:5], v[196:199], v[228:231], v[2:5]
	s_barrier
	s_add_i32 s84, 0, 0x18000
	v_add_u32_e32 v162, s84, v151
	s_add_i32 s85, 0, 0x1c000
	ds_read_b128 v[164:167], v162
	ds_read_b128 v[168:171], v162 offset:1024
	ds_read_b128 v[172:175], v162 offset:2048
	ds_read_b128 v[176:179], v162 offset:3072
	v_add_u32_e32 v162, s85, v151
	ds_read_b128 v[184:187], v162
	ds_read_b128 v[188:191], v162 offset:1024
	ds_read_b128 v[192:195], v162 offset:2048
	ds_read_b128 v[196:199], v162 offset:3072
	s_add_u32 s34, s34, 0x100000
	s_addc_u32 s35, s35, 0
	s_mov_b32 m0, s47
	v_lshl_add_u64 v[236:237], s[34:35], 0, v[130:131]
	ds_read_b128 v[200:203], v161 offset:32768
	ds_read_b128 v[204:207], v161 offset:33792
	ds_read_b128 v[208:211], v161 offset:34816
	ds_read_b128 v[212:215], v161 offset:35840
	ds_read_b128 v[216:219], v161 offset:36864
	ds_read_b128 v[220:223], v161 offset:37888
	ds_read_b128 v[224:227], v161 offset:38912
	ds_read_b128 v[228:231], v161 offset:39936
	global_load_lds_dwordx4 v[236:237], off
	v_lshl_add_u64 v[236:237], s[34:35], 0, v[134:135]
	s_mov_b32 m0, s50
	s_nop 0
	global_load_lds_dwordx4 v[236:237], off
	s_waitcnt vmcnt(8)
	s_waitcnt lgkmcnt(0)
	s_barrier
	s_waitcnt lgkmcnt(0)
	v_mfma_f32_16x16x32_bf16 v[126:129], v[164:167], v[200:203], v[126:129]
	v_mfma_f32_16x16x32_bf16 v[126:129], v[168:171], v[204:207], v[126:129]
	v_mfma_f32_16x16x32_bf16 v[118:121], v[164:167], v[208:211], v[118:121]
	v_mfma_f32_16x16x32_bf16 v[118:121], v[168:171], v[212:215], v[118:121]
	v_mfma_f32_16x16x32_bf16 v[102:105], v[164:167], v[216:219], v[102:105]
	v_mfma_f32_16x16x32_bf16 v[102:105], v[168:171], v[220:223], v[102:105]
	v_mfma_f32_16x16x32_bf16 v[86:89], v[164:167], v[224:227], v[86:89]
	v_mfma_f32_16x16x32_bf16 v[86:89], v[168:171], v[228:231], v[86:89]
	v_mfma_f32_16x16x32_bf16 v[114:117], v[184:187], v[200:203], v[114:117]
	v_mfma_f32_16x16x32_bf16 v[114:117], v[188:191], v[204:207], v[114:117]
	v_mfma_f32_16x16x32_bf16 v[98:101], v[184:187], v[208:211], v[98:101]
	v_mfma_f32_16x16x32_bf16 v[98:101], v[188:191], v[212:215], v[98:101]
	v_mfma_f32_16x16x32_bf16 v[82:85], v[184:187], v[216:219], v[82:85]
	v_mfma_f32_16x16x32_bf16 v[82:85], v[188:191], v[220:223], v[82:85]
	v_mfma_f32_16x16x32_bf16 v[70:73], v[184:187], v[224:227], v[70:73]
	v_mfma_f32_16x16x32_bf16 v[70:73], v[188:191], v[228:231], v[70:73]
	v_mfma_f32_16x16x32_bf16 v[122:125], v[172:175], v[200:203], v[122:125]
	v_mfma_f32_16x16x32_bf16 v[122:125], v[176:179], v[204:207], v[122:125]
	v_mfma_f32_16x16x32_bf16 v[110:113], v[172:175], v[208:211], v[110:113]
	v_mfma_f32_16x16x32_bf16 v[110:113], v[176:179], v[212:215], v[110:113]
	v_mfma_f32_16x16x32_bf16 v[94:97], v[172:175], v[216:219], v[94:97]
	v_mfma_f32_16x16x32_bf16 v[94:97], v[176:179], v[220:223], v[94:97]
	v_mfma_f32_16x16x32_bf16 v[78:81], v[172:175], v[224:227], v[78:81]
	v_mfma_f32_16x16x32_bf16 v[78:81], v[176:179], v[228:231], v[78:81]
	v_mfma_f32_16x16x32_bf16 v[106:109], v[192:195], v[200:203], v[106:109]
	v_mfma_f32_16x16x32_bf16 v[106:109], v[196:199], v[204:207], v[106:109]
	v_mfma_f32_16x16x32_bf16 v[90:93], v[192:195], v[208:211], v[90:93]
	v_mfma_f32_16x16x32_bf16 v[90:93], v[196:199], v[212:215], v[90:93]
	v_mfma_f32_16x16x32_bf16 v[74:77], v[192:195], v[216:219], v[74:77]
	v_mfma_f32_16x16x32_bf16 v[74:77], v[196:199], v[220:223], v[74:77]
	v_mfma_f32_16x16x32_bf16 v[66:69], v[192:195], v[224:227], v[66:69]
	v_mfma_f32_16x16x32_bf16 v[66:69], v[196:199], v[228:231], v[66:69]
	s_barrier
	s_add_i32 s34, s84, s43
	v_lshl_add_u64 v[148:149], v[148:149], 0, s[14:15]
	s_mov_b32 m0, s34
	ds_read_b128 v[200:203], v161 offset:49152
	ds_read_b128 v[204:207], v161 offset:50176
	ds_read_b128 v[208:211], v161 offset:51200
	ds_read_b128 v[212:215], v161 offset:52224
	ds_read_b128 v[216:219], v161 offset:53248
	ds_read_b128 v[220:223], v161 offset:54272
	ds_read_b128 v[224:227], v161 offset:55296
	ds_read_b128 v[228:231], v161 offset:56320
	global_load_lds_dwordx4 v[148:149], off
	s_add_i32 m0, s34, 0x2000
	s_add_u32 s30, s30, 0x100080
	v_lshl_add_u64 v[148:149], v[180:181], 0, s[14:15]
	s_addc_u32 s31, s31, 0
	s_add_i32 s34, s85, s43
	global_load_lds_dwordx4 v[148:149], off
	v_lshl_add_u64 v[148:149], s[30:31], 0, v[132:133]
	s_mov_b32 m0, s34
	s_nop 0
	global_load_lds_dwordx4 v[148:149], off
	v_lshl_add_u64 v[148:149], s[30:31], 0, v[136:137]
	s_add_i32 m0, s34, 0x2000
	s_nop 0
	global_load_lds_dwordx4 v[148:149], off
	v_lshl_add_u64 v[148:149], v[232:233], 0, s[14:15]
	s_mov_b32 m0, s52
	s_nop 0
	global_load_lds_dwordx4 v[148:149], off
	v_lshl_add_u64 v[148:149], v[234:235], 0, s[14:15]
	s_mov_b32 m0, s53
	s_nop 0
	global_load_lds_dwordx4 v[148:149], off
	s_waitcnt vmcnt(8)
	s_waitcnt lgkmcnt(0)
	s_barrier
	s_waitcnt lgkmcnt(0)
	v_mfma_f32_16x16x32_bf16 v[62:65], v[164:167], v[200:203], v[62:65]
	v_mfma_f32_16x16x32_bf16 v[62:65], v[168:171], v[204:207], v[62:65]
	v_mfma_f32_16x16x32_bf16 v[54:57], v[164:167], v[208:211], v[54:57]
	v_mfma_f32_16x16x32_bf16 v[54:57], v[168:171], v[212:215], v[54:57]
	v_mfma_f32_16x16x32_bf16 v[38:41], v[164:167], v[216:219], v[38:41]
	v_mfma_f32_16x16x32_bf16 v[38:41], v[168:171], v[220:223], v[38:41]
	v_mfma_f32_16x16x32_bf16 v[22:25], v[164:167], v[224:227], v[22:25]
	v_mfma_f32_16x16x32_bf16 v[22:25], v[168:171], v[228:231], v[22:25]
	v_mfma_f32_16x16x32_bf16 v[50:53], v[184:187], v[200:203], v[50:53]
	v_mfma_f32_16x16x32_bf16 v[50:53], v[188:191], v[204:207], v[50:53]
	v_mfma_f32_16x16x32_bf16 v[34:37], v[184:187], v[208:211], v[34:37]
	v_mfma_f32_16x16x32_bf16 v[34:37], v[188:191], v[212:215], v[34:37]
	v_mfma_f32_16x16x32_bf16 v[18:21], v[184:187], v[216:219], v[18:21]
	v_mfma_f32_16x16x32_bf16 v[18:21], v[188:191], v[220:223], v[18:21]
	v_mfma_f32_16x16x32_bf16 v[6:9], v[184:187], v[224:227], v[6:9]
	v_mfma_f32_16x16x32_bf16 v[6:9], v[188:191], v[228:231], v[6:9]
	v_mfma_f32_16x16x32_bf16 v[58:61], v[172:175], v[200:203], v[58:61]
	v_mfma_f32_16x16x32_bf16 v[58:61], v[176:179], v[204:207], v[58:61]
	v_mfma_f32_16x16x32_bf16 v[46:49], v[172:175], v[208:211], v[46:49]
	v_mfma_f32_16x16x32_bf16 v[46:49], v[176:179], v[212:215], v[46:49]
	v_mfma_f32_16x16x32_bf16 v[30:33], v[172:175], v[216:219], v[30:33]
	v_mfma_f32_16x16x32_bf16 v[30:33], v[176:179], v[220:223], v[30:33]
	v_mfma_f32_16x16x32_bf16 v[14:17], v[172:175], v[224:227], v[14:17]
	v_mfma_f32_16x16x32_bf16 v[14:17], v[176:179], v[228:231], v[14:17]
	v_mfma_f32_16x16x32_bf16 v[42:45], v[192:195], v[200:203], v[42:45]
	v_mfma_f32_16x16x32_bf16 v[42:45], v[196:199], v[204:207], v[42:45]
	v_mfma_f32_16x16x32_bf16 v[26:29], v[192:195], v[208:211], v[26:29]
	v_mfma_f32_16x16x32_bf16 v[26:29], v[196:199], v[212:215], v[26:29]
	v_mfma_f32_16x16x32_bf16 v[10:13], v[192:195], v[216:219], v[10:13]
	v_mfma_f32_16x16x32_bf16 v[10:13], v[196:199], v[220:223], v[10:13]
	v_mfma_f32_16x16x32_bf16 v[2:5], v[192:195], v[224:227], v[2:5]
	v_mfma_f32_16x16x32_bf16 v[2:5], v[196:199], v[228:231], v[2:5]
	s_barrier
	s_add_i32 s83, s83, 2
	s_add_u32 s28, s28, 0x100
	s_addc_u32 s29, s29, 0
	s_add_u32 s81, s81, 0x100
	s_addc_u32 s82, s82, 0
	s_cmp_gt_u32 s83, 61
	s_cbranch_scc0 .LBB0_217
	s_and_b64 vcc, exec, s[16:17]
	s_cbranch_vccz .LBB0_220
	s_barrier

.LBB0_237:
	ds_read_b128 v[148:151], v164
	ds_read_b128 v[168:171], v164 offset:1024
	ds_read_b128 v[172:175], v164 offset:2048
	ds_read_b128 v[176:179], v164 offset:3072
	ds_read_b128 v[184:187], v165
	ds_read_b128 v[188:191], v165 offset:1024
	ds_read_b128 v[192:195], v165 offset:2048
	ds_read_b128 v[196:199], v165 offset:3072
	s_add_u32 s28, s26, 0xfff00080
	s_addc_u32 s29, s27, -1
	s_cmp_eq_u32 s63, 60
	s_cselect_b32 s31, s19, s29
	s_cselect_b32 s30, s53, s28
	s_cselect_b32 s29, s17, s62
	s_cselect_b32 s28, s58, s59
	v_lshl_add_u64 v[152:153], s[26:27], 0, v[140:141]
	s_add_i32 m0, s25, 0xc000
	ds_read_b128 v[200:203], v166
	ds_read_b128 v[204:207], v166 offset:1024
	ds_read_b128 v[208:211], v166 offset:2048
	ds_read_b128 v[212:215], v166 offset:3072
	ds_read_b128 v[216:219], v166 offset:4096
	ds_read_b128 v[220:223], v166 offset:5120
	ds_read_b128 v[224:227], v166 offset:6144
	ds_read_b128 v[228:231], v166 offset:7168
	global_load_lds_dwordx4 v[152:153], off
	v_lshl_add_u64 v[152:153], s[26:27], 0, v[142:143]
	s_add_i32 m0, s25, 0xe000
	s_nop 0
	global_load_lds_dwordx4 v[152:153], off
	s_waitcnt vmcnt(8)
	s_waitcnt lgkmcnt(0)
	s_barrier
	s_waitcnt lgkmcnt(0)
	v_mfma_f32_16x16x32_bf16 v[126:129], v[148:151], v[200:203], v[126:129]
	v_mfma_f32_16x16x32_bf16 v[126:129], v[168:171], v[204:207], v[126:129]
	v_mfma_f32_16x16x32_bf16 v[110:113], v[148:151], v[208:211], v[110:113]
	v_mfma_f32_16x16x32_bf16 v[110:113], v[168:171], v[212:215], v[110:113]
	v_mfma_f32_16x16x32_bf16 v[94:97], v[148:151], v[216:219], v[94:97]
	v_mfma_f32_16x16x32_bf16 v[94:97], v[168:171], v[220:223], v[94:97]
	v_mfma_f32_16x16x32_bf16 v[78:81], v[148:151], v[224:227], v[78:81]
	v_mfma_f32_16x16x32_bf16 v[78:81], v[168:171], v[228:231], v[78:81]
	v_mfma_f32_16x16x32_bf16 v[118:121], v[184:187], v[200:203], v[118:121]
	v_mfma_f32_16x16x32_bf16 v[118:121], v[188:191], v[204:207], v[118:121]
	v_mfma_f32_16x16x32_bf16 v[102:105], v[184:187], v[208:211], v[102:105]
	v_mfma_f32_16x16x32_bf16 v[102:105], v[188:191], v[212:215], v[102:105]
	v_mfma_f32_16x16x32_bf16 v[86:89], v[184:187], v[216:219], v[86:89]
	v_mfma_f32_16x16x32_bf16 v[86:89], v[188:191], v[220:223], v[86:89]
	v_mfma_f32_16x16x32_bf16 v[70:73], v[184:187], v[224:227], v[70:73]
	v_mfma_f32_16x16x32_bf16 v[70:73], v[188:191], v[228:231], v[70:73]
	v_mfma_f32_16x16x32_bf16 v[122:125], v[172:175], v[200:203], v[122:125]
	v_mfma_f32_16x16x32_bf16 v[122:125], v[176:179], v[204:207], v[122:125]
	v_mfma_f32_16x16x32_bf16 v[106:109], v[172:175], v[208:211], v[106:109]
	v_mfma_f32_16x16x32_bf16 v[106:109], v[176:179], v[212:215], v[106:109]
	v_mfma_f32_16x16x32_bf16 v[90:93], v[172:175], v[216:219], v[90:93]
	v_mfma_f32_16x16x32_bf16 v[90:93], v[176:179], v[220:223], v[90:93]
	v_mfma_f32_16x16x32_bf16 v[74:77], v[172:175], v[224:227], v[74:77]
	v_mfma_f32_16x16x32_bf16 v[74:77], v[176:179], v[228:231], v[74:77]
	v_mfma_f32_16x16x32_bf16 v[114:117], v[192:195], v[200:203], v[114:117]
	v_mfma_f32_16x16x32_bf16 v[114:117], v[196:199], v[204:207], v[114:117]
	v_mfma_f32_16x16x32_bf16 v[98:101], v[192:195], v[208:211], v[98:101]
	v_mfma_f32_16x16x32_bf16 v[98:101], v[196:199], v[212:215], v[98:101]
	v_mfma_f32_16x16x32_bf16 v[82:85], v[192:195], v[216:219], v[82:85]
	v_mfma_f32_16x16x32_bf16 v[82:85], v[196:199], v[220:223], v[82:85]
	v_mfma_f32_16x16x32_bf16 v[66:69], v[192:195], v[224:227], v[66:69]
	v_mfma_f32_16x16x32_bf16 v[66:69], v[196:199], v[228:231], v[66:69]
	s_barrier
	s_add_i32 s80, s50, s34
	v_lshl_add_u64 v[152:153], s[28:29], 0, v[132:133]
	s_mov_b32 m0, s80
	ds_read_b128 v[200:203], v166 offset:16384
	ds_read_b128 v[204:207], v166 offset:17408
	ds_read_b128 v[208:211], v166 offset:18432
	ds_read_b128 v[212:215], v166 offset:19456
	ds_read_b128 v[216:219], v166 offset:20480
	ds_read_b128 v[220:223], v166 offset:21504
	ds_read_b128 v[224:227], v166 offset:22528
	ds_read_b128 v[228:231], v166 offset:23552
	global_load_lds_dwordx4 v[152:153], off
	s_add_i32 m0, s80, 0x2000
	s_add_u32 s80, s28, 0x100000
	v_lshl_add_u64 v[180:181], s[28:29], 0, v[136:137]
	s_addc_u32 s81, s29, 0
	s_add_i32 s82, s51, s34
	global_load_lds_dwordx4 v[180:181], off
	v_lshl_add_u64 v[232:233], s[80:81], 0, v[132:133]
	s_mov_b32 m0, s82
	v_lshl_add_u64 v[234:235], s[30:31], 0, v[134:135]
	global_load_lds_dwordx4 v[232:233], off
	v_lshl_add_u64 v[232:233], s[80:81], 0, v[136:137]
	s_add_i32 m0, s82, 0x2000
	s_nop 0
	global_load_lds_dwordx4 v[232:233], off
	v_lshl_add_u64 v[232:233], s[30:31], 0, v[130:131]
	s_mov_b32 m0, s25
	s_nop 0
	global_load_lds_dwordx4 v[232:233], off
	s_mov_b32 m0, s41
	s_nop 0
	global_load_lds_dwordx4 v[234:235], off
	s_waitcnt vmcnt(8)
	s_waitcnt lgkmcnt(0)
	s_barrier
	s_waitcnt lgkmcnt(0)
	v_mfma_f32_16x16x32_bf16 v[62:65], v[148:151], v[200:203], v[62:65]
	v_mfma_f32_16x16x32_bf16 v[62:65], v[168:171], v[204:207], v[62:65]
	v_mfma_f32_16x16x32_bf16 v[46:49], v[148:151], v[208:211], v[46:49]
	v_mfma_f32_16x16x32_bf16 v[46:49], v[168:171], v[212:215], v[46:49]
	v_mfma_f32_16x16x32_bf16 v[30:33], v[148:151], v[216:219], v[30:33]
	v_mfma_f32_16x16x32_bf16 v[30:33], v[168:171], v[220:223], v[30:33]
	v_mfma_f32_16x16x32_bf16 v[14:17], v[148:151], v[224:227], v[14:17]
	v_mfma_f32_16x16x32_bf16 v[14:17], v[168:171], v[228:231], v[14:17]
	v_mfma_f32_16x16x32_bf16 v[54:57], v[184:187], v[200:203], v[54:57]
	v_mfma_f32_16x16x32_bf16 v[54:57], v[188:191], v[204:207], v[54:57]
	v_mfma_f32_16x16x32_bf16 v[38:41], v[184:187], v[208:211], v[38:41]
	v_mfma_f32_16x16x32_bf16 v[38:41], v[188:191], v[212:215], v[38:41]
	v_mfma_f32_16x16x32_bf16 v[22:25], v[184:187], v[216:219], v[22:25]
	v_mfma_f32_16x16x32_bf16 v[22:25], v[188:191], v[220:223], v[22:25]
	v_mfma_f32_16x16x32_bf16 v[6:9], v[184:187], v[224:227], v[6:9]
	v_mfma_f32_16x16x32_bf16 v[6:9], v[188:191], v[228:231], v[6:9]
	v_mfma_f32_16x16x32_bf16 v[58:61], v[172:175], v[200:203], v[58:61]
	v_mfma_f32_16x16x32_bf16 v[58:61], v[176:179], v[204:207], v[58:61]
	v_mfma_f32_16x16x32_bf16 v[42:45], v[172:175], v[208:211], v[42:45]
	v_mfma_f32_16x16x32_bf16 v[42:45], v[176:179], v[212:215], v[42:45]
	v_mfma_f32_16x16x32_bf16 v[26:29], v[172:175], v[216:219], v[26:29]
	v_mfma_f32_16x16x32_bf16 v[26:29], v[176:179], v[220:223], v[26:29]
	v_mfma_f32_16x16x32_bf16 v[10:13], v[172:175], v[224:227], v[10:13]
	v_mfma_f32_16x16x32_bf16 v[10:13], v[176:179], v[228:231], v[10:13]
	v_mfma_f32_16x16x32_bf16 v[50:53], v[192:195], v[200:203], v[50:53]
	v_mfma_f32_16x16x32_bf16 v[50:53], v[196:199], v[204:207], v[50:53]
	v_mfma_f32_16x16x32_bf16 v[34:37], v[192:195], v[208:211], v[34:37]
	v_mfma_f32_16x16x32_bf16 v[34:37], v[196:199], v[212:215], v[34:37]
	v_mfma_f32_16x16x32_bf16 v[18:21], v[192:195], v[216:219], v[18:21]
	v_mfma_f32_16x16x32_bf16 v[18:21], v[196:199], v[220:223], v[18:21]
	v_mfma_f32_16x16x32_bf16 v[2:5], v[192:195], v[224:227], v[2:5]
	v_mfma_f32_16x16x32_bf16 v[2:5], v[196:199], v[228:231], v[2:5]
	s_barrier
	s_add_i32 s80, 0, 0x18000
	v_add_u32_e32 v167, s80, v161
	s_add_i32 s81, 0, 0x1c000
	ds_read_b128 v[148:151], v167
	ds_read_b128 v[168:171], v167 offset:1024
	ds_read_b128 v[172:175], v167 offset:2048
	ds_read_b128 v[176:179], v167 offset:3072
	v_add_u32_e32 v167, s81, v161
	ds_read_b128 v[184:187], v167
	ds_read_b128 v[188:191], v167 offset:1024
	ds_read_b128 v[192:195], v167 offset:2048
	ds_read_b128 v[196:199], v167 offset:3072
	s_add_u32 s30, s30, 0x100000
	s_addc_u32 s31, s31, 0
	s_mov_b32 m0, s42
	v_lshl_add_u64 v[236:237], s[30:31], 0, v[130:131]
	ds_read_b128 v[200:203], v166 offset:32768
	ds_read_b128 v[204:207], v166 offset:33792
	ds_read_b128 v[208:211], v166 offset:34816
	ds_read_b128 v[212:215], v166 offset:35840
	ds_read_b128 v[216:219], v166 offset:36864
	ds_read_b128 v[220:223], v166 offset:37888
	ds_read_b128 v[224:227], v166 offset:38912
	ds_read_b128 v[228:231], v166 offset:39936
	global_load_lds_dwordx4 v[236:237], off
	v_lshl_add_u64 v[236:237], s[30:31], 0, v[134:135]
	s_mov_b32 m0, s44
	s_nop 0
	global_load_lds_dwordx4 v[236:237], off
	s_waitcnt vmcnt(8)
	s_waitcnt lgkmcnt(0)
	s_barrier
	s_waitcnt lgkmcnt(0)
	v_mfma_f32_16x16x32_bf16 v[126:129], v[148:151], v[200:203], v[126:129]
	v_mfma_f32_16x16x32_bf16 v[126:129], v[168:171], v[204:207], v[126:129]
	v_mfma_f32_16x16x32_bf16 v[110:113], v[148:151], v[208:211], v[110:113]
	v_mfma_f32_16x16x32_bf16 v[110:113], v[168:171], v[212:215], v[110:113]
	v_mfma_f32_16x16x32_bf16 v[94:97], v[148:151], v[216:219], v[94:97]
	v_mfma_f32_16x16x32_bf16 v[94:97], v[168:171], v[220:223], v[94:97]
	v_mfma_f32_16x16x32_bf16 v[78:81], v[148:151], v[224:227], v[78:81]
	v_mfma_f32_16x16x32_bf16 v[78:81], v[168:171], v[228:231], v[78:81]
	v_mfma_f32_16x16x32_bf16 v[118:121], v[184:187], v[200:203], v[118:121]
	v_mfma_f32_16x16x32_bf16 v[118:121], v[188:191], v[204:207], v[118:121]
	v_mfma_f32_16x16x32_bf16 v[102:105], v[184:187], v[208:211], v[102:105]
	v_mfma_f32_16x16x32_bf16 v[102:105], v[188:191], v[212:215], v[102:105]
	v_mfma_f32_16x16x32_bf16 v[86:89], v[184:187], v[216:219], v[86:89]
	v_mfma_f32_16x16x32_bf16 v[86:89], v[188:191], v[220:223], v[86:89]
	v_mfma_f32_16x16x32_bf16 v[70:73], v[184:187], v[224:227], v[70:73]
	v_mfma_f32_16x16x32_bf16 v[70:73], v[188:191], v[228:231], v[70:73]
	v_mfma_f32_16x16x32_bf16 v[122:125], v[172:175], v[200:203], v[122:125]
	v_mfma_f32_16x16x32_bf16 v[122:125], v[176:179], v[204:207], v[122:125]
	v_mfma_f32_16x16x32_bf16 v[106:109], v[172:175], v[208:211], v[106:109]
	v_mfma_f32_16x16x32_bf16 v[106:109], v[176:179], v[212:215], v[106:109]
	v_mfma_f32_16x16x32_bf16 v[90:93], v[172:175], v[216:219], v[90:93]
	v_mfma_f32_16x16x32_bf16 v[90:93], v[176:179], v[220:223], v[90:93]
	v_mfma_f32_16x16x32_bf16 v[74:77], v[172:175], v[224:227], v[74:77]
	v_mfma_f32_16x16x32_bf16 v[74:77], v[176:179], v[228:231], v[74:77]
	v_mfma_f32_16x16x32_bf16 v[114:117], v[192:195], v[200:203], v[114:117]
	v_mfma_f32_16x16x32_bf16 v[114:117], v[196:199], v[204:207], v[114:117]
	v_mfma_f32_16x16x32_bf16 v[98:101], v[192:195], v[208:211], v[98:101]
	v_mfma_f32_16x16x32_bf16 v[98:101], v[196:199], v[212:215], v[98:101]
	v_mfma_f32_16x16x32_bf16 v[82:85], v[192:195], v[216:219], v[82:85]
	v_mfma_f32_16x16x32_bf16 v[82:85], v[196:199], v[220:223], v[82:85]
	v_mfma_f32_16x16x32_bf16 v[66:69], v[192:195], v[224:227], v[66:69]
	v_mfma_f32_16x16x32_bf16 v[66:69], v[196:199], v[228:231], v[66:69]
	s_barrier
	s_add_i32 s30, s80, s34
	v_lshl_add_u64 v[152:153], v[152:153], 0, s[12:13]
	s_mov_b32 m0, s30
	ds_read_b128 v[200:203], v166 offset:49152
	ds_read_b128 v[204:207], v166 offset:50176
	ds_read_b128 v[208:211], v166 offset:51200
	ds_read_b128 v[212:215], v166 offset:52224
	ds_read_b128 v[216:219], v166 offset:53248
	ds_read_b128 v[220:223], v166 offset:54272
	ds_read_b128 v[224:227], v166 offset:55296
	ds_read_b128 v[228:231], v166 offset:56320
	global_load_lds_dwordx4 v[152:153], off
	s_add_i32 m0, s30, 0x2000
	s_add_u32 s28, s28, 0x100080
	v_lshl_add_u64 v[152:153], v[180:181], 0, s[12:13]
	s_addc_u32 s29, s29, 0
	s_add_i32 s30, s81, s34
	global_load_lds_dwordx4 v[152:153], off
	v_lshl_add_u64 v[152:153], s[28:29], 0, v[132:133]
	s_mov_b32 m0, s30
	s_nop 0
	global_load_lds_dwordx4 v[152:153], off
	v_lshl_add_u64 v[152:153], s[28:29], 0, v[136:137]
	s_add_i32 m0, s30, 0x2000
	s_nop 0
	global_load_lds_dwordx4 v[152:153], off
	v_lshl_add_u64 v[152:153], v[232:233], 0, s[12:13]
	s_mov_b32 m0, s46
	s_nop 0
	global_load_lds_dwordx4 v[152:153], off
	v_lshl_add_u64 v[152:153], v[234:235], 0, s[12:13]
	s_mov_b32 m0, s47
	s_nop 0
	global_load_lds_dwordx4 v[152:153], off
	s_waitcnt vmcnt(8)
	s_waitcnt lgkmcnt(0)
	s_barrier
	s_waitcnt lgkmcnt(0)
	v_mfma_f32_16x16x32_bf16 v[62:65], v[148:151], v[200:203], v[62:65]
	v_mfma_f32_16x16x32_bf16 v[62:65], v[168:171], v[204:207], v[62:65]
	v_mfma_f32_16x16x32_bf16 v[46:49], v[148:151], v[208:211], v[46:49]
	v_mfma_f32_16x16x32_bf16 v[46:49], v[168:171], v[212:215], v[46:49]
	v_mfma_f32_16x16x32_bf16 v[30:33], v[148:151], v[216:219], v[30:33]
	v_mfma_f32_16x16x32_bf16 v[30:33], v[168:171], v[220:223], v[30:33]
	v_mfma_f32_16x16x32_bf16 v[14:17], v[148:151], v[224:227], v[14:17]
	v_mfma_f32_16x16x32_bf16 v[14:17], v[168:171], v[228:231], v[14:17]
	v_mfma_f32_16x16x32_bf16 v[54:57], v[184:187], v[200:203], v[54:57]
	v_mfma_f32_16x16x32_bf16 v[54:57], v[188:191], v[204:207], v[54:57]
	v_mfma_f32_16x16x32_bf16 v[38:41], v[184:187], v[208:211], v[38:41]
	v_mfma_f32_16x16x32_bf16 v[38:41], v[188:191], v[212:215], v[38:41]
	v_mfma_f32_16x16x32_bf16 v[22:25], v[184:187], v[216:219], v[22:25]
	v_mfma_f32_16x16x32_bf16 v[22:25], v[188:191], v[220:223], v[22:25]
	v_mfma_f32_16x16x32_bf16 v[6:9], v[184:187], v[224:227], v[6:9]
	v_mfma_f32_16x16x32_bf16 v[6:9], v[188:191], v[228:231], v[6:9]
	v_mfma_f32_16x16x32_bf16 v[58:61], v[172:175], v[200:203], v[58:61]
	v_mfma_f32_16x16x32_bf16 v[58:61], v[176:179], v[204:207], v[58:61]
	v_mfma_f32_16x16x32_bf16 v[42:45], v[172:175], v[208:211], v[42:45]
	v_mfma_f32_16x16x32_bf16 v[42:45], v[176:179], v[212:215], v[42:45]
	v_mfma_f32_16x16x32_bf16 v[26:29], v[172:175], v[216:219], v[26:29]
	v_mfma_f32_16x16x32_bf16 v[26:29], v[176:179], v[220:223], v[26:29]
	v_mfma_f32_16x16x32_bf16 v[10:13], v[172:175], v[224:227], v[10:13]
	v_mfma_f32_16x16x32_bf16 v[10:13], v[176:179], v[228:231], v[10:13]
	v_mfma_f32_16x16x32_bf16 v[50:53], v[192:195], v[200:203], v[50:53]
	v_mfma_f32_16x16x32_bf16 v[50:53], v[196:199], v[204:207], v[50:53]
	v_mfma_f32_16x16x32_bf16 v[34:37], v[192:195], v[208:211], v[34:37]
	v_mfma_f32_16x16x32_bf16 v[34:37], v[196:199], v[212:215], v[34:37]
	v_mfma_f32_16x16x32_bf16 v[18:21], v[192:195], v[216:219], v[18:21]
	v_mfma_f32_16x16x32_bf16 v[18:21], v[196:199], v[220:223], v[18:21]
	v_mfma_f32_16x16x32_bf16 v[2:5], v[192:195], v[224:227], v[2:5]
	v_mfma_f32_16x16x32_bf16 v[2:5], v[196:199], v[228:231], v[2:5]
	s_barrier
	s_add_i32 s63, s63, 2
	s_add_u32 s26, s26, 0x100
	s_addc_u32 s27, s27, 0
	s_add_u32 s59, s59, 0x100
	s_addc_u32 s62, s62, 0
	s_cmp_gt_u32 s63, 61
	s_cbranch_scc0 .LBB0_237
	s_and_b64 vcc, exec, s[14:15]
	s_cbranch_vccz .LBB0_240
	s_barrier

.LBB0_269:
	v_add_u32_e32 v147, s46, v161
	ds_read_b128 v[166:169], v147
	ds_read_b128 v[170:173], v147 offset:1024
	ds_read_b128 v[174:177], v147 offset:2048
	ds_read_b128 v[178:181], v147 offset:3072
	v_add_u32_e32 v147, s47, v161
	ds_read_b128 v[184:187], v147
	ds_read_b128 v[188:191], v147 offset:1024
	ds_read_b128 v[192:195], v147 offset:2048
	ds_read_b128 v[196:199], v147 offset:3072
	s_mov_b32 s34, 0xfff00080
	s_cmp_eq_u32 s30, 60
	s_mov_b32 s35, -1
	v_lshl_add_u64 v[200:201], v[156:157], 0, s[34:35]
	s_cselect_b64 vcc, -1, 0
	v_cndmask_b32_e32 v233, v201, v1, vcc
	v_cndmask_b32_e32 v232, v200, v152, vcc
	v_cndmask_b32_e32 v235, v159, v145, vcc
	v_cndmask_b32_e32 v234, v158, v154, vcc
	v_lshl_add_u64 v[236:237], v[156:157], 0, v[138:139]
	s_add_i32 m0, s39, 0xc000
	ds_read_b128 v[200:203], v155
	ds_read_b128 v[204:207], v155 offset:1024
	ds_read_b128 v[208:211], v155 offset:2048
	ds_read_b128 v[212:215], v155 offset:3072
	ds_read_b128 v[216:219], v155 offset:4096
	ds_read_b128 v[220:223], v155 offset:5120
	ds_read_b128 v[224:227], v155 offset:6144
	ds_read_b128 v[228:231], v155 offset:7168
	global_load_lds_dwordx4 v[236:237], off
	v_lshl_add_u64 v[236:237], v[156:157], 0, v[140:141]
	s_add_i32 m0, s39, 0xe000
	s_nop 0
	global_load_lds_dwordx4 v[236:237], off
	s_waitcnt vmcnt(8)
	s_waitcnt lgkmcnt(0)
	s_barrier
	s_waitcnt lgkmcnt(0)
	v_mfma_f32_16x16x32_bf16 v[126:129], v[166:169], v[200:203], v[126:129]
	v_mfma_f32_16x16x32_bf16 v[126:129], v[170:173], v[204:207], v[126:129]
	v_mfma_f32_16x16x32_bf16 v[118:121], v[166:169], v[208:211], v[118:121]
	v_mfma_f32_16x16x32_bf16 v[118:121], v[170:173], v[212:215], v[118:121]
	v_mfma_f32_16x16x32_bf16 v[102:105], v[166:169], v[216:219], v[102:105]
	v_mfma_f32_16x16x32_bf16 v[102:105], v[170:173], v[220:223], v[102:105]
	v_mfma_f32_16x16x32_bf16 v[86:89], v[166:169], v[224:227], v[86:89]
	v_mfma_f32_16x16x32_bf16 v[86:89], v[170:173], v[228:231], v[86:89]
	v_mfma_f32_16x16x32_bf16 v[114:117], v[184:187], v[200:203], v[114:117]
	v_mfma_f32_16x16x32_bf16 v[114:117], v[188:191], v[204:207], v[114:117]
	v_mfma_f32_16x16x32_bf16 v[98:101], v[184:187], v[208:211], v[98:101]
	v_mfma_f32_16x16x32_bf16 v[98:101], v[188:191], v[212:215], v[98:101]
	v_mfma_f32_16x16x32_bf16 v[82:85], v[184:187], v[216:219], v[82:85]
	v_mfma_f32_16x16x32_bf16 v[82:85], v[188:191], v[220:223], v[82:85]
	v_mfma_f32_16x16x32_bf16 v[70:73], v[184:187], v[224:227], v[70:73]
	v_mfma_f32_16x16x32_bf16 v[70:73], v[188:191], v[228:231], v[70:73]
	v_mfma_f32_16x16x32_bf16 v[122:125], v[174:177], v[200:203], v[122:125]
	v_mfma_f32_16x16x32_bf16 v[122:125], v[178:181], v[204:207], v[122:125]
	v_mfma_f32_16x16x32_bf16 v[110:113], v[174:177], v[208:211], v[110:113]
	v_mfma_f32_16x16x32_bf16 v[110:113], v[178:181], v[212:215], v[110:113]
	v_mfma_f32_16x16x32_bf16 v[94:97], v[174:177], v[216:219], v[94:97]
	v_mfma_f32_16x16x32_bf16 v[94:97], v[178:181], v[220:223], v[94:97]
	v_mfma_f32_16x16x32_bf16 v[78:81], v[174:177], v[224:227], v[78:81]
	v_mfma_f32_16x16x32_bf16 v[78:81], v[178:181], v[228:231], v[78:81]
	v_mfma_f32_16x16x32_bf16 v[106:109], v[192:195], v[200:203], v[106:109]
	v_mfma_f32_16x16x32_bf16 v[106:109], v[196:199], v[204:207], v[106:109]
	v_mfma_f32_16x16x32_bf16 v[90:93], v[192:195], v[208:211], v[90:93]
	v_mfma_f32_16x16x32_bf16 v[90:93], v[196:199], v[212:215], v[90:93]
	v_mfma_f32_16x16x32_bf16 v[74:77], v[192:195], v[216:219], v[74:77]
	v_mfma_f32_16x16x32_bf16 v[74:77], v[196:199], v[220:223], v[74:77]
	v_mfma_f32_16x16x32_bf16 v[66:69], v[192:195], v[224:227], v[66:69]
	v_mfma_f32_16x16x32_bf16 v[66:69], v[196:199], v[228:231], v[66:69]
	s_barrier
	s_add_i32 s31, s46, s38
	v_lshl_add_u64 v[236:237], v[234:235], 0, v[132:133]
	s_mov_b32 m0, s31
	ds_read_b128 v[200:203], v155 offset:16384
	ds_read_b128 v[204:207], v155 offset:17408
	ds_read_b128 v[208:211], v155 offset:18432
	ds_read_b128 v[212:215], v155 offset:19456
	ds_read_b128 v[216:219], v155 offset:20480
	ds_read_b128 v[220:223], v155 offset:21504
	ds_read_b128 v[224:227], v155 offset:22528
	ds_read_b128 v[228:231], v155 offset:23552
	global_load_lds_dwordx4 v[236:237], off
	v_lshl_add_u64 v[238:239], v[234:235], 0, v[136:137]
	s_add_i32 m0, s31, 0x2000
	v_lshl_add_u64 v[240:241], v[234:235], 0, s[6:7]
	s_add_i32 s31, s47, s38
	global_load_lds_dwordx4 v[238:239], off
	v_lshl_add_u64 v[242:243], v[240:241], 0, v[132:133]
	s_mov_b32 m0, s31
	v_lshl_add_u64 v[240:241], v[240:241], 0, v[136:137]
	global_load_lds_dwordx4 v[242:243], off
	s_add_i32 m0, s31, 0x2000
	v_lshl_add_u64 v[242:243], v[232:233], 0, v[134:135]
	global_load_lds_dwordx4 v[240:241], off
	v_lshl_add_u64 v[240:241], v[232:233], 0, v[130:131]
	s_mov_b32 m0, s39
	s_nop 0
	global_load_lds_dwordx4 v[240:241], off
	s_mov_b32 m0, s40
	s_nop 0
	global_load_lds_dwordx4 v[242:243], off
	s_waitcnt vmcnt(8)
	s_waitcnt lgkmcnt(0)
	s_barrier
	s_waitcnt lgkmcnt(0)
	v_mfma_f32_16x16x32_bf16 v[62:65], v[166:169], v[200:203], v[62:65]
	v_mfma_f32_16x16x32_bf16 v[62:65], v[170:173], v[204:207], v[62:65]
	v_mfma_f32_16x16x32_bf16 v[54:57], v[166:169], v[208:211], v[54:57]
	v_mfma_f32_16x16x32_bf16 v[54:57], v[170:173], v[212:215], v[54:57]
	v_mfma_f32_16x16x32_bf16 v[38:41], v[166:169], v[216:219], v[38:41]
	v_mfma_f32_16x16x32_bf16 v[38:41], v[170:173], v[220:223], v[38:41]
	v_mfma_f32_16x16x32_bf16 v[22:25], v[166:169], v[224:227], v[22:25]
	v_mfma_f32_16x16x32_bf16 v[22:25], v[170:173], v[228:231], v[22:25]
	v_mfma_f32_16x16x32_bf16 v[50:53], v[184:187], v[200:203], v[50:53]
	v_mfma_f32_16x16x32_bf16 v[50:53], v[188:191], v[204:207], v[50:53]
	v_mfma_f32_16x16x32_bf16 v[34:37], v[184:187], v[208:211], v[34:37]
	v_mfma_f32_16x16x32_bf16 v[34:37], v[188:191], v[212:215], v[34:37]
	v_mfma_f32_16x16x32_bf16 v[18:21], v[184:187], v[216:219], v[18:21]
	v_mfma_f32_16x16x32_bf16 v[18:21], v[188:191], v[220:223], v[18:21]
	v_mfma_f32_16x16x32_bf16 v[6:9], v[184:187], v[224:227], v[6:9]
	v_mfma_f32_16x16x32_bf16 v[6:9], v[188:191], v[228:231], v[6:9]
	v_mfma_f32_16x16x32_bf16 v[58:61], v[174:177], v[200:203], v[58:61]
	v_mfma_f32_16x16x32_bf16 v[58:61], v[178:181], v[204:207], v[58:61]
	v_mfma_f32_16x16x32_bf16 v[46:49], v[174:177], v[208:211], v[46:49]
	v_mfma_f32_16x16x32_bf16 v[46:49], v[178:181], v[212:215], v[46:49]
	v_mfma_f32_16x16x32_bf16 v[30:33], v[174:177], v[216:219], v[30:33]
	v_mfma_f32_16x16x32_bf16 v[30:33], v[178:181], v[220:223], v[30:33]
	v_mfma_f32_16x16x32_bf16 v[14:17], v[174:177], v[224:227], v[14:17]
	v_mfma_f32_16x16x32_bf16 v[14:17], v[178:181], v[228:231], v[14:17]
	v_mfma_f32_16x16x32_bf16 v[42:45], v[192:195], v[200:203], v[42:45]
	v_mfma_f32_16x16x32_bf16 v[42:45], v[196:199], v[204:207], v[42:45]
	v_mfma_f32_16x16x32_bf16 v[26:29], v[192:195], v[208:211], v[26:29]
	v_mfma_f32_16x16x32_bf16 v[26:29], v[196:199], v[212:215], v[26:29]
	v_mfma_f32_16x16x32_bf16 v[10:13], v[192:195], v[216:219], v[10:13]
	v_mfma_f32_16x16x32_bf16 v[10:13], v[196:199], v[220:223], v[10:13]
	v_mfma_f32_16x16x32_bf16 v[2:5], v[192:195], v[224:227], v[2:5]
	v_mfma_f32_16x16x32_bf16 v[2:5], v[196:199], v[228:231], v[2:5]
	s_barrier
	s_add_i32 s31, 0, 0x18000
	v_add_u32_e32 v147, s31, v161
	s_add_i32 s34, 0, 0x1c000
	ds_read_b128 v[166:169], v147
	ds_read_b128 v[170:173], v147 offset:1024
	ds_read_b128 v[174:177], v147 offset:2048
	ds_read_b128 v[178:181], v147 offset:3072
	v_add_u32_e32 v147, s34, v161
	ds_read_b128 v[184:187], v147
	ds_read_b128 v[188:191], v147 offset:1024
	ds_read_b128 v[192:195], v147 offset:2048
	ds_read_b128 v[196:199], v147 offset:3072
	v_lshl_add_u64 v[232:233], v[232:233], 0, s[6:7]
	s_mov_b32 m0, s41
	v_lshl_add_u64 v[244:245], v[232:233], 0, v[130:131]
	ds_read_b128 v[200:203], v155 offset:32768
	ds_read_b128 v[204:207], v155 offset:33792
	ds_read_b128 v[208:211], v155 offset:34816
	ds_read_b128 v[212:215], v155 offset:35840
	ds_read_b128 v[216:219], v155 offset:36864
	ds_read_b128 v[220:223], v155 offset:37888
	ds_read_b128 v[224:227], v155 offset:38912
	ds_read_b128 v[228:231], v155 offset:39936
	global_load_lds_dwordx4 v[244:245], off
	v_lshl_add_u64 v[232:233], v[232:233], 0, v[134:135]
	s_mov_b32 m0, s42
	s_nop 0
	global_load_lds_dwordx4 v[232:233], off
	s_waitcnt vmcnt(8)
	s_waitcnt lgkmcnt(0)
	s_barrier
	s_waitcnt lgkmcnt(0)
	v_mfma_f32_16x16x32_bf16 v[126:129], v[166:169], v[200:203], v[126:129]
	v_mfma_f32_16x16x32_bf16 v[126:129], v[170:173], v[204:207], v[126:129]
	v_mfma_f32_16x16x32_bf16 v[118:121], v[166:169], v[208:211], v[118:121]
	v_mfma_f32_16x16x32_bf16 v[118:121], v[170:173], v[212:215], v[118:121]
	v_mfma_f32_16x16x32_bf16 v[102:105], v[166:169], v[216:219], v[102:105]
	v_mfma_f32_16x16x32_bf16 v[102:105], v[170:173], v[220:223], v[102:105]
	v_mfma_f32_16x16x32_bf16 v[86:89], v[166:169], v[224:227], v[86:89]
	v_mfma_f32_16x16x32_bf16 v[86:89], v[170:173], v[228:231], v[86:89]
	v_mfma_f32_16x16x32_bf16 v[114:117], v[184:187], v[200:203], v[114:117]
	v_mfma_f32_16x16x32_bf16 v[114:117], v[188:191], v[204:207], v[114:117]
	v_mfma_f32_16x16x32_bf16 v[98:101], v[184:187], v[208:211], v[98:101]
	v_mfma_f32_16x16x32_bf16 v[98:101], v[188:191], v[212:215], v[98:101]
	v_mfma_f32_16x16x32_bf16 v[82:85], v[184:187], v[216:219], v[82:85]
	v_mfma_f32_16x16x32_bf16 v[82:85], v[188:191], v[220:223], v[82:85]
	v_mfma_f32_16x16x32_bf16 v[70:73], v[184:187], v[224:227], v[70:73]
	v_mfma_f32_16x16x32_bf16 v[70:73], v[188:191], v[228:231], v[70:73]
	v_mfma_f32_16x16x32_bf16 v[122:125], v[174:177], v[200:203], v[122:125]
	v_mfma_f32_16x16x32_bf16 v[122:125], v[178:181], v[204:207], v[122:125]
	v_mfma_f32_16x16x32_bf16 v[110:113], v[174:177], v[208:211], v[110:113]
	v_mfma_f32_16x16x32_bf16 v[110:113], v[178:181], v[212:215], v[110:113]
	v_mfma_f32_16x16x32_bf16 v[94:97], v[174:177], v[216:219], v[94:97]
	v_mfma_f32_16x16x32_bf16 v[94:97], v[178:181], v[220:223], v[94:97]
	v_mfma_f32_16x16x32_bf16 v[78:81], v[174:177], v[224:227], v[78:81]
	v_mfma_f32_16x16x32_bf16 v[78:81], v[178:181], v[228:231], v[78:81]
	v_mfma_f32_16x16x32_bf16 v[106:109], v[192:195], v[200:203], v[106:109]
	v_mfma_f32_16x16x32_bf16 v[106:109], v[196:199], v[204:207], v[106:109]
	v_mfma_f32_16x16x32_bf16 v[90:93], v[192:195], v[208:211], v[90:93]
	v_mfma_f32_16x16x32_bf16 v[90:93], v[196:199], v[212:215], v[90:93]
	v_mfma_f32_16x16x32_bf16 v[74:77], v[192:195], v[216:219], v[74:77]
	v_mfma_f32_16x16x32_bf16 v[74:77], v[196:199], v[220:223], v[74:77]
	v_mfma_f32_16x16x32_bf16 v[66:69], v[192:195], v[224:227], v[66:69]
	v_mfma_f32_16x16x32_bf16 v[66:69], v[196:199], v[228:231], v[66:69]
	s_barrier
	s_add_i32 s31, s31, s38
	v_lshl_add_u64 v[232:233], v[236:237], 0, s[12:13]
	s_mov_b32 m0, s31
	ds_read_b128 v[200:203], v155 offset:49152
	ds_read_b128 v[204:207], v155 offset:50176
	ds_read_b128 v[208:211], v155 offset:51200
	ds_read_b128 v[212:215], v155 offset:52224
	ds_read_b128 v[216:219], v155 offset:53248
	ds_read_b128 v[220:223], v155 offset:54272
	ds_read_b128 v[224:227], v155 offset:55296
	ds_read_b128 v[228:231], v155 offset:56320
	global_load_lds_dwordx4 v[232:233], off
	v_lshl_add_u64 v[232:233], v[238:239], 0, s[12:13]
	s_add_i32 m0, s31, 0x2000
	s_add_i32 s31, s34, s38
	global_load_lds_dwordx4 v[232:233], off
	v_lshl_add_u64 v[232:233], v[234:235], 0, s[16:17]
	v_lshl_add_u64 v[234:235], v[232:233], 0, v[132:133]
	s_mov_b32 m0, s31
	v_lshl_add_u64 v[232:233], v[232:233], 0, v[136:137]
	global_load_lds_dwordx4 v[234:235], off
	s_add_i32 m0, s31, 0x2000
	s_nop 0
	global_load_lds_dwordx4 v[232:233], off
	v_lshl_add_u64 v[232:233], v[240:241], 0, s[12:13]
	s_mov_b32 m0, s44
	s_nop 0
	global_load_lds_dwordx4 v[232:233], off
	v_lshl_add_u64 v[232:233], v[242:243], 0, s[12:13]
	s_mov_b32 m0, s45
	s_nop 0
	global_load_lds_dwordx4 v[232:233], off
	s_waitcnt vmcnt(8)
	s_waitcnt lgkmcnt(0)
	s_barrier
	s_waitcnt lgkmcnt(0)
	v_mfma_f32_16x16x32_bf16 v[62:65], v[166:169], v[200:203], v[62:65]
	v_mfma_f32_16x16x32_bf16 v[62:65], v[170:173], v[204:207], v[62:65]
	v_mfma_f32_16x16x32_bf16 v[54:57], v[166:169], v[208:211], v[54:57]
	v_mfma_f32_16x16x32_bf16 v[54:57], v[170:173], v[212:215], v[54:57]
	v_mfma_f32_16x16x32_bf16 v[38:41], v[166:169], v[216:219], v[38:41]
	v_mfma_f32_16x16x32_bf16 v[38:41], v[170:173], v[220:223], v[38:41]
	v_mfma_f32_16x16x32_bf16 v[22:25], v[166:169], v[224:227], v[22:25]
	v_mfma_f32_16x16x32_bf16 v[22:25], v[170:173], v[228:231], v[22:25]
	v_mfma_f32_16x16x32_bf16 v[50:53], v[184:187], v[200:203], v[50:53]
	v_mfma_f32_16x16x32_bf16 v[50:53], v[188:191], v[204:207], v[50:53]
	v_mfma_f32_16x16x32_bf16 v[34:37], v[184:187], v[208:211], v[34:37]
	v_mfma_f32_16x16x32_bf16 v[34:37], v[188:191], v[212:215], v[34:37]
	v_mfma_f32_16x16x32_bf16 v[18:21], v[184:187], v[216:219], v[18:21]
	v_mfma_f32_16x16x32_bf16 v[18:21], v[188:191], v[220:223], v[18:21]
	v_mfma_f32_16x16x32_bf16 v[6:9], v[184:187], v[224:227], v[6:9]
	v_mfma_f32_16x16x32_bf16 v[6:9], v[188:191], v[228:231], v[6:9]
	v_mfma_f32_16x16x32_bf16 v[58:61], v[174:177], v[200:203], v[58:61]
	v_mfma_f32_16x16x32_bf16 v[58:61], v[178:181], v[204:207], v[58:61]
	v_mfma_f32_16x16x32_bf16 v[46:49], v[174:177], v[208:211], v[46:49]
	v_mfma_f32_16x16x32_bf16 v[46:49], v[178:181], v[212:215], v[46:49]
	v_mfma_f32_16x16x32_bf16 v[30:33], v[174:177], v[216:219], v[30:33]
	v_mfma_f32_16x16x32_bf16 v[30:33], v[178:181], v[220:223], v[30:33]
	v_mfma_f32_16x16x32_bf16 v[14:17], v[174:177], v[224:227], v[14:17]
	v_mfma_f32_16x16x32_bf16 v[14:17], v[178:181], v[228:231], v[14:17]
	v_mfma_f32_16x16x32_bf16 v[42:45], v[192:195], v[200:203], v[42:45]
	v_mfma_f32_16x16x32_bf16 v[42:45], v[196:199], v[204:207], v[42:45]
	v_mfma_f32_16x16x32_bf16 v[26:29], v[192:195], v[208:211], v[26:29]
	v_mfma_f32_16x16x32_bf16 v[26:29], v[196:199], v[212:215], v[26:29]
	v_mfma_f32_16x16x32_bf16 v[10:13], v[192:195], v[216:219], v[10:13]
	v_mfma_f32_16x16x32_bf16 v[10:13], v[196:199], v[220:223], v[10:13]
	v_mfma_f32_16x16x32_bf16 v[2:5], v[192:195], v[224:227], v[2:5]
	v_mfma_f32_16x16x32_bf16 v[2:5], v[196:199], v[228:231], v[2:5]
	s_barrier
	s_add_i32 s30, s30, 2
	v_lshl_add_u64 v[156:157], v[156:157], 0, s[22:23]
	s_cmp_gt_u32 s30, 61
	v_lshl_add_u64 v[158:159], v[158:159], 0, s[22:23]
	s_cbranch_scc0 .LBB0_269
	s_and_b64 vcc, exec, s[18:19]
	s_cbranch_vccz .LBB0_272
	s_barrier

.LBB0_763:
	ds_read_b128 v[142:145], v165
	ds_read_b128 v[146:149], v165 offset:1024
	ds_read_b128 v[150:153], v165 offset:2048
	ds_read_b128 v[154:157], v165 offset:3072
	ds_read_b128 v[158:161], v166
	ds_read_b128 v[168:171], v166 offset:1024
	ds_read_b128 v[172:175], v166 offset:2048
	ds_read_b128 v[176:179], v166 offset:3072
	s_add_u32 s28, s26, 0xffe00080
	s_addc_u32 s29, s27, -1
	s_cmpk_eq_i32 s59, 0x7c
	s_cselect_b32 s31, s19, s29
	s_cselect_b32 s30, s53, s28
	s_cselect_b32 s29, s17, s58
	s_cselect_b32 s28, s56, s57
	v_lshl_add_u64 v[180:181], s[26:27], 0, v[134:135]
	s_add_i32 m0, s25, 0xc000
	ds_read_b128 v[184:187], v167
	ds_read_b128 v[188:191], v167 offset:1024
	ds_read_b128 v[192:195], v167 offset:2048
	ds_read_b128 v[196:199], v167 offset:3072
	ds_read_b128 v[200:203], v167 offset:4096
	ds_read_b128 v[204:207], v167 offset:5120
	ds_read_b128 v[208:211], v167 offset:6144
	ds_read_b128 v[212:215], v167 offset:7168
	global_load_lds_dwordx4 v[180:181], off
	v_lshl_add_u64 v[180:181], s[26:27], 0, v[136:137]
	s_add_i32 m0, s25, 0xe000
	s_nop 0
	global_load_lds_dwordx4 v[180:181], off
	s_waitcnt vmcnt(8)
	s_waitcnt lgkmcnt(0)
	s_barrier
	s_waitcnt lgkmcnt(0)
	v_mfma_f32_16x16x32_bf16 v[126:129], v[142:145], v[184:187], v[126:129]
	v_mfma_f32_16x16x32_bf16 v[126:129], v[146:149], v[188:191], v[126:129]
	v_mfma_f32_16x16x32_bf16 v[114:117], v[142:145], v[192:195], v[114:117]
	v_mfma_f32_16x16x32_bf16 v[114:117], v[146:149], v[196:199], v[114:117]
	v_mfma_f32_16x16x32_bf16 v[98:101], v[142:145], v[200:203], v[98:101]
	v_mfma_f32_16x16x32_bf16 v[98:101], v[146:149], v[204:207], v[98:101]
	v_mfma_f32_16x16x32_bf16 v[82:85], v[142:145], v[208:211], v[82:85]
	v_mfma_f32_16x16x32_bf16 v[82:85], v[146:149], v[212:215], v[82:85]
	v_mfma_f32_16x16x32_bf16 v[118:121], v[158:161], v[184:187], v[118:121]
	v_mfma_f32_16x16x32_bf16 v[118:121], v[168:171], v[188:191], v[118:121]
	v_mfma_f32_16x16x32_bf16 v[102:105], v[158:161], v[192:195], v[102:105]
	v_mfma_f32_16x16x32_bf16 v[102:105], v[168:171], v[196:199], v[102:105]
	v_mfma_f32_16x16x32_bf16 v[86:89], v[158:161], v[200:203], v[86:89]
	v_mfma_f32_16x16x32_bf16 v[86:89], v[168:171], v[204:207], v[86:89]
	v_mfma_f32_16x16x32_bf16 v[70:73], v[158:161], v[208:211], v[70:73]
	v_mfma_f32_16x16x32_bf16 v[70:73], v[168:171], v[212:215], v[70:73]
	v_mfma_f32_16x16x32_bf16 v[122:125], v[150:153], v[184:187], v[122:125]
	v_mfma_f32_16x16x32_bf16 v[122:125], v[154:157], v[188:191], v[122:125]
	v_mfma_f32_16x16x32_bf16 v[106:109], v[150:153], v[192:195], v[106:109]
	v_mfma_f32_16x16x32_bf16 v[106:109], v[154:157], v[196:199], v[106:109]
	v_mfma_f32_16x16x32_bf16 v[90:93], v[150:153], v[200:203], v[90:93]
	v_mfma_f32_16x16x32_bf16 v[90:93], v[154:157], v[204:207], v[90:93]
	v_mfma_f32_16x16x32_bf16 v[74:77], v[150:153], v[208:211], v[74:77]
	v_mfma_f32_16x16x32_bf16 v[74:77], v[154:157], v[212:215], v[74:77]
	v_mfma_f32_16x16x32_bf16 v[110:113], v[172:175], v[184:187], v[110:113]
	v_mfma_f32_16x16x32_bf16 v[110:113], v[176:179], v[188:191], v[110:113]
	v_mfma_f32_16x16x32_bf16 v[94:97], v[172:175], v[192:195], v[94:97]
	v_mfma_f32_16x16x32_bf16 v[94:97], v[176:179], v[196:199], v[94:97]
	v_mfma_f32_16x16x32_bf16 v[78:81], v[172:175], v[200:203], v[78:81]
	v_mfma_f32_16x16x32_bf16 v[78:81], v[176:179], v[204:207], v[78:81]
	v_mfma_f32_16x16x32_bf16 v[66:69], v[172:175], v[208:211], v[66:69]
	v_mfma_f32_16x16x32_bf16 v[66:69], v[176:179], v[212:215], v[66:69]
	s_barrier
	s_add_i32 s60, s50, s38
	v_lshl_add_u64 v[180:181], s[28:29], 0, v[130:131]
	s_mov_b32 m0, s60
	ds_read_b128 v[184:187], v167 offset:16384
	ds_read_b128 v[188:191], v167 offset:17408
	ds_read_b128 v[192:195], v167 offset:18432
	ds_read_b128 v[196:199], v167 offset:19456
	ds_read_b128 v[200:203], v167 offset:20480
	ds_read_b128 v[204:207], v167 offset:21504
	ds_read_b128 v[208:211], v167 offset:22528
	ds_read_b128 v[212:215], v167 offset:23552
	global_load_lds_dwordx4 v[180:181], off
	s_add_i32 m0, s60, 0x2000
	s_add_u32 s60, s28, 0x200000
	v_lshl_add_u64 v[216:217], s[28:29], 0, v[132:133]
	s_addc_u32 s61, s29, 0
	s_add_i32 s62, s51, s38
	global_load_lds_dwordx4 v[216:217], off
	v_lshl_add_u64 v[218:219], s[60:61], 0, v[130:131]
	s_mov_b32 m0, s62
	v_lshl_add_u64 v[220:221], s[30:31], 0, v[132:133]
	global_load_lds_dwordx4 v[218:219], off
	v_lshl_add_u64 v[218:219], s[60:61], 0, v[132:133]
	s_add_i32 m0, s62, 0x2000
	s_nop 0
	global_load_lds_dwordx4 v[218:219], off
	v_lshl_add_u64 v[218:219], s[30:31], 0, v[130:131]
	s_mov_b32 m0, s25
	s_nop 0
	global_load_lds_dwordx4 v[218:219], off
	s_mov_b32 m0, s40
	s_nop 0
	global_load_lds_dwordx4 v[220:221], off
	s_waitcnt vmcnt(8)
	s_waitcnt lgkmcnt(0)
	s_barrier
	s_waitcnt lgkmcnt(0)
	v_mfma_f32_16x16x32_bf16 v[62:65], v[142:145], v[184:187], v[62:65]
	v_mfma_f32_16x16x32_bf16 v[62:65], v[146:149], v[188:191], v[62:65]
	v_mfma_f32_16x16x32_bf16 v[50:53], v[142:145], v[192:195], v[50:53]
	v_mfma_f32_16x16x32_bf16 v[50:53], v[146:149], v[196:199], v[50:53]
	v_mfma_f32_16x16x32_bf16 v[34:37], v[142:145], v[200:203], v[34:37]
	v_mfma_f32_16x16x32_bf16 v[34:37], v[146:149], v[204:207], v[34:37]
	v_mfma_f32_16x16x32_bf16 v[18:21], v[142:145], v[208:211], v[18:21]
	v_mfma_f32_16x16x32_bf16 v[18:21], v[146:149], v[212:215], v[18:21]
	v_mfma_f32_16x16x32_bf16 v[54:57], v[158:161], v[184:187], v[54:57]
	v_mfma_f32_16x16x32_bf16 v[54:57], v[168:171], v[188:191], v[54:57]
	v_mfma_f32_16x16x32_bf16 v[38:41], v[158:161], v[192:195], v[38:41]
	v_mfma_f32_16x16x32_bf16 v[38:41], v[168:171], v[196:199], v[38:41]
	v_mfma_f32_16x16x32_bf16 v[22:25], v[158:161], v[200:203], v[22:25]
	v_mfma_f32_16x16x32_bf16 v[22:25], v[168:171], v[204:207], v[22:25]
	v_mfma_f32_16x16x32_bf16 v[6:9], v[158:161], v[208:211], v[6:9]
	v_mfma_f32_16x16x32_bf16 v[6:9], v[168:171], v[212:215], v[6:9]
	v_mfma_f32_16x16x32_bf16 v[58:61], v[150:153], v[184:187], v[58:61]
	v_mfma_f32_16x16x32_bf16 v[58:61], v[154:157], v[188:191], v[58:61]
	v_mfma_f32_16x16x32_bf16 v[42:45], v[150:153], v[192:195], v[42:45]
	v_mfma_f32_16x16x32_bf16 v[42:45], v[154:157], v[196:199], v[42:45]
	v_mfma_f32_16x16x32_bf16 v[26:29], v[150:153], v[200:203], v[26:29]
	v_mfma_f32_16x16x32_bf16 v[26:29], v[154:157], v[204:207], v[26:29]
	v_mfma_f32_16x16x32_bf16 v[10:13], v[150:153], v[208:211], v[10:13]
	v_mfma_f32_16x16x32_bf16 v[10:13], v[154:157], v[212:215], v[10:13]
	v_mfma_f32_16x16x32_bf16 v[46:49], v[172:175], v[184:187], v[46:49]
	v_mfma_f32_16x16x32_bf16 v[46:49], v[176:179], v[188:191], v[46:49]
	v_mfma_f32_16x16x32_bf16 v[30:33], v[172:175], v[192:195], v[30:33]
	v_mfma_f32_16x16x32_bf16 v[30:33], v[176:179], v[196:199], v[30:33]
	v_mfma_f32_16x16x32_bf16 v[14:17], v[172:175], v[200:203], v[14:17]
	v_mfma_f32_16x16x32_bf16 v[14:17], v[176:179], v[204:207], v[14:17]
	v_mfma_f32_16x16x32_bf16 v[2:5], v[172:175], v[208:211], v[2:5]
	v_mfma_f32_16x16x32_bf16 v[2:5], v[176:179], v[212:215], v[2:5]
	s_barrier
	s_add_i32 s60, 0, 0x18000
	s_add_i32 s61, 0, 0x1c000
	v_add_u32_e32 v154, s60, v162
	v_add_u32_e32 v176, s61, v162
	ds_read_b128 v[142:145], v154
	ds_read_b128 v[146:149], v154 offset:1024
	ds_read_b128 v[150:153], v154 offset:2048
	ds_read_b128 v[154:157], v154 offset:3072
	ds_read_b128 v[158:161], v176
	ds_read_b128 v[168:171], v176 offset:1024
	ds_read_b128 v[172:175], v176 offset:2048
	ds_read_b128 v[176:179], v176 offset:3072
	s_add_u32 s30, s30, 0x200000
	s_addc_u32 s31, s31, 0
	s_mov_b32 m0, s41
	v_lshl_add_u64 v[222:223], s[30:31], 0, v[130:131]
	ds_read_b128 v[184:187], v167 offset:32768
	ds_read_b128 v[188:191], v167 offset:33792
	ds_read_b128 v[192:195], v167 offset:34816
	ds_read_b128 v[196:199], v167 offset:35840
	ds_read_b128 v[200:203], v167 offset:36864
	ds_read_b128 v[204:207], v167 offset:37888
	ds_read_b128 v[208:211], v167 offset:38912
	ds_read_b128 v[212:215], v167 offset:39936
	global_load_lds_dwordx4 v[222:223], off
	v_lshl_add_u64 v[222:223], s[30:31], 0, v[132:133]
	s_mov_b32 m0, s42
	s_nop 0
	global_load_lds_dwordx4 v[222:223], off
	s_waitcnt vmcnt(8)
	s_waitcnt lgkmcnt(0)
	s_barrier
	s_waitcnt lgkmcnt(0)
	v_mfma_f32_16x16x32_bf16 v[126:129], v[142:145], v[184:187], v[126:129]
	v_mfma_f32_16x16x32_bf16 v[126:129], v[146:149], v[188:191], v[126:129]
	v_mfma_f32_16x16x32_bf16 v[114:117], v[142:145], v[192:195], v[114:117]
	v_mfma_f32_16x16x32_bf16 v[114:117], v[146:149], v[196:199], v[114:117]
	v_mfma_f32_16x16x32_bf16 v[98:101], v[142:145], v[200:203], v[98:101]
	v_mfma_f32_16x16x32_bf16 v[98:101], v[146:149], v[204:207], v[98:101]
	v_mfma_f32_16x16x32_bf16 v[82:85], v[142:145], v[208:211], v[82:85]
	v_mfma_f32_16x16x32_bf16 v[82:85], v[146:149], v[212:215], v[82:85]
	v_mfma_f32_16x16x32_bf16 v[118:121], v[158:161], v[184:187], v[118:121]
	v_mfma_f32_16x16x32_bf16 v[118:121], v[168:171], v[188:191], v[118:121]
	v_mfma_f32_16x16x32_bf16 v[102:105], v[158:161], v[192:195], v[102:105]
	v_mfma_f32_16x16x32_bf16 v[102:105], v[168:171], v[196:199], v[102:105]
	v_mfma_f32_16x16x32_bf16 v[86:89], v[158:161], v[200:203], v[86:89]
	v_mfma_f32_16x16x32_bf16 v[86:89], v[168:171], v[204:207], v[86:89]
	v_mfma_f32_16x16x32_bf16 v[70:73], v[158:161], v[208:211], v[70:73]
	v_mfma_f32_16x16x32_bf16 v[70:73], v[168:171], v[212:215], v[70:73]
	v_mfma_f32_16x16x32_bf16 v[122:125], v[150:153], v[184:187], v[122:125]
	v_mfma_f32_16x16x32_bf16 v[122:125], v[154:157], v[188:191], v[122:125]
	v_mfma_f32_16x16x32_bf16 v[106:109], v[150:153], v[192:195], v[106:109]
	v_mfma_f32_16x16x32_bf16 v[106:109], v[154:157], v[196:199], v[106:109]
	v_mfma_f32_16x16x32_bf16 v[90:93], v[150:153], v[200:203], v[90:93]
	v_mfma_f32_16x16x32_bf16 v[90:93], v[154:157], v[204:207], v[90:93]
	v_mfma_f32_16x16x32_bf16 v[74:77], v[150:153], v[208:211], v[74:77]
	v_mfma_f32_16x16x32_bf16 v[74:77], v[154:157], v[212:215], v[74:77]
	v_mfma_f32_16x16x32_bf16 v[110:113], v[172:175], v[184:187], v[110:113]
	v_mfma_f32_16x16x32_bf16 v[110:113], v[176:179], v[188:191], v[110:113]
	v_mfma_f32_16x16x32_bf16 v[94:97], v[172:175], v[192:195], v[94:97]
	v_mfma_f32_16x16x32_bf16 v[94:97], v[176:179], v[196:199], v[94:97]
	v_mfma_f32_16x16x32_bf16 v[78:81], v[172:175], v[200:203], v[78:81]
	v_mfma_f32_16x16x32_bf16 v[78:81], v[176:179], v[204:207], v[78:81]
	v_mfma_f32_16x16x32_bf16 v[66:69], v[172:175], v[208:211], v[66:69]
	v_mfma_f32_16x16x32_bf16 v[66:69], v[176:179], v[212:215], v[66:69]
	s_barrier
	s_add_i32 s30, s60, s38
	v_lshl_add_u64 v[180:181], v[180:181], 0, s[10:11]
	s_mov_b32 m0, s30
	ds_read_b128 v[184:187], v167 offset:49152
	ds_read_b128 v[188:191], v167 offset:50176
	ds_read_b128 v[192:195], v167 offset:51200
	ds_read_b128 v[196:199], v167 offset:52224
	ds_read_b128 v[200:203], v167 offset:53248
	ds_read_b128 v[204:207], v167 offset:54272
	ds_read_b128 v[208:211], v167 offset:55296
	ds_read_b128 v[212:215], v167 offset:56320
	global_load_lds_dwordx4 v[180:181], off
	s_add_i32 m0, s30, 0x2000
	s_add_u32 s28, s28, 0x200080
	v_lshl_add_u64 v[180:181], v[216:217], 0, s[10:11]
	s_addc_u32 s29, s29, 0
	s_add_i32 s30, s61, s38
	global_load_lds_dwordx4 v[180:181], off
	v_lshl_add_u64 v[180:181], s[28:29], 0, v[130:131]
	s_mov_b32 m0, s30
	s_nop 0
	global_load_lds_dwordx4 v[180:181], off
	v_lshl_add_u64 v[180:181], s[28:29], 0, v[132:133]
	s_add_i32 m0, s30, 0x2000
	s_nop 0
	global_load_lds_dwordx4 v[180:181], off
	v_lshl_add_u64 v[180:181], v[218:219], 0, s[10:11]
	s_mov_b32 m0, s45
	s_nop 0
	global_load_lds_dwordx4 v[180:181], off
	v_lshl_add_u64 v[180:181], v[220:221], 0, s[10:11]
	s_mov_b32 m0, s46
	s_nop 0
	global_load_lds_dwordx4 v[180:181], off
	s_waitcnt vmcnt(8)
	s_waitcnt lgkmcnt(0)
	s_barrier
	s_waitcnt lgkmcnt(0)
	v_mfma_f32_16x16x32_bf16 v[62:65], v[142:145], v[184:187], v[62:65]
	v_mfma_f32_16x16x32_bf16 v[62:65], v[146:149], v[188:191], v[62:65]
	v_mfma_f32_16x16x32_bf16 v[50:53], v[142:145], v[192:195], v[50:53]
	v_mfma_f32_16x16x32_bf16 v[50:53], v[146:149], v[196:199], v[50:53]
	v_mfma_f32_16x16x32_bf16 v[34:37], v[142:145], v[200:203], v[34:37]
	v_mfma_f32_16x16x32_bf16 v[34:37], v[146:149], v[204:207], v[34:37]
	v_mfma_f32_16x16x32_bf16 v[18:21], v[142:145], v[208:211], v[18:21]
	v_mfma_f32_16x16x32_bf16 v[18:21], v[146:149], v[212:215], v[18:21]
	v_mfma_f32_16x16x32_bf16 v[54:57], v[158:161], v[184:187], v[54:57]
	v_mfma_f32_16x16x32_bf16 v[54:57], v[168:171], v[188:191], v[54:57]
	v_mfma_f32_16x16x32_bf16 v[38:41], v[158:161], v[192:195], v[38:41]
	v_mfma_f32_16x16x32_bf16 v[38:41], v[168:171], v[196:199], v[38:41]
	v_mfma_f32_16x16x32_bf16 v[22:25], v[158:161], v[200:203], v[22:25]
	v_mfma_f32_16x16x32_bf16 v[22:25], v[168:171], v[204:207], v[22:25]
	v_mfma_f32_16x16x32_bf16 v[6:9], v[158:161], v[208:211], v[6:9]
	v_mfma_f32_16x16x32_bf16 v[6:9], v[168:171], v[212:215], v[6:9]
	v_mfma_f32_16x16x32_bf16 v[58:61], v[150:153], v[184:187], v[58:61]
	v_mfma_f32_16x16x32_bf16 v[58:61], v[154:157], v[188:191], v[58:61]
	v_mfma_f32_16x16x32_bf16 v[42:45], v[150:153], v[192:195], v[42:45]
	v_mfma_f32_16x16x32_bf16 v[42:45], v[154:157], v[196:199], v[42:45]
	v_mfma_f32_16x16x32_bf16 v[26:29], v[150:153], v[200:203], v[26:29]
	v_mfma_f32_16x16x32_bf16 v[26:29], v[154:157], v[204:207], v[26:29]
	v_mfma_f32_16x16x32_bf16 v[10:13], v[150:153], v[208:211], v[10:13]
	v_mfma_f32_16x16x32_bf16 v[10:13], v[154:157], v[212:215], v[10:13]
	v_mfma_f32_16x16x32_bf16 v[46:49], v[172:175], v[184:187], v[46:49]
	v_mfma_f32_16x16x32_bf16 v[46:49], v[176:179], v[188:191], v[46:49]
	v_mfma_f32_16x16x32_bf16 v[30:33], v[172:175], v[192:195], v[30:33]
	v_mfma_f32_16x16x32_bf16 v[30:33], v[176:179], v[196:199], v[30:33]
	v_mfma_f32_16x16x32_bf16 v[14:17], v[172:175], v[200:203], v[14:17]
	v_mfma_f32_16x16x32_bf16 v[14:17], v[176:179], v[204:207], v[14:17]
	v_mfma_f32_16x16x32_bf16 v[2:5], v[172:175], v[208:211], v[2:5]
	v_mfma_f32_16x16x32_bf16 v[2:5], v[176:179], v[212:215], v[2:5]
	s_barrier
	s_add_i32 s59, s59, 2
	s_add_u32 s26, s26, 0x100
	s_addc_u32 s27, s27, 0
	s_add_u32 s57, s57, 0x100
	s_addc_u32 s58, s58, 0
	s_cmpk_gt_u32 s59, 0x7d
	s_cbranch_scc0 .LBB0_763
	s_and_b64 vcc, exec, s[14:15]
	s_cbranch_vccz .LBB0_766
	s_barrier

.LBB0_916:
	ds_read_b128 v[164:167], v158
	ds_read_b128 v[168:171], v158 offset:1024
	ds_read_b128 v[172:175], v158 offset:2048
	ds_read_b128 v[176:179], v158 offset:3072
	ds_read_b128 v[180:183], v159
	ds_read_b128 v[184:187], v159 offset:1024
	ds_read_b128 v[188:191], v159 offset:2048
	ds_read_b128 v[192:195], v159 offset:3072
	s_add_u32 s28, s26, 0xfff00080
	s_addc_u32 s29, s27, -1
	s_cmp_eq_u32 s59, 60
	s_cselect_b32 s31, s19, s29
	s_cselect_b32 s30, s53, s28
	s_cselect_b32 s29, s17, s58
	s_cselect_b32 s28, s56, s57
	v_lshl_add_u64 v[146:147], s[26:27], 0, v[138:139]
	s_add_i32 m0, s25, 0xc000
	ds_read_b128 v[196:199], v160
	ds_read_b128 v[200:203], v160 offset:1024
	ds_read_b128 v[204:207], v160 offset:2048
	ds_read_b128 v[208:211], v160 offset:3072
	ds_read_b128 v[212:215], v160 offset:4096
	ds_read_b128 v[216:219], v160 offset:5120
	ds_read_b128 v[220:223], v160 offset:6144
	ds_read_b128 v[224:227], v160 offset:7168
	global_load_lds_dwordx4 v[146:147], off
	v_lshl_add_u64 v[146:147], s[26:27], 0, v[140:141]
	s_add_i32 m0, s25, 0xe000
	s_nop 0
	global_load_lds_dwordx4 v[146:147], off
	s_waitcnt vmcnt(8)
	s_waitcnt lgkmcnt(0)
	s_barrier
	s_waitcnt lgkmcnt(0)
	v_mfma_f32_16x16x32_bf16 v[126:129], v[164:167], v[196:199], v[126:129]
	v_mfma_f32_16x16x32_bf16 v[126:129], v[168:171], v[200:203], v[126:129]
	v_mfma_f32_16x16x32_bf16 v[110:113], v[164:167], v[204:207], v[110:113]
	v_mfma_f32_16x16x32_bf16 v[110:113], v[168:171], v[208:211], v[110:113]
	v_mfma_f32_16x16x32_bf16 v[94:97], v[164:167], v[212:215], v[94:97]
	v_mfma_f32_16x16x32_bf16 v[94:97], v[168:171], v[216:219], v[94:97]
	v_mfma_f32_16x16x32_bf16 v[78:81], v[164:167], v[220:223], v[78:81]
	v_mfma_f32_16x16x32_bf16 v[78:81], v[168:171], v[224:227], v[78:81]
	v_mfma_f32_16x16x32_bf16 v[118:121], v[180:183], v[196:199], v[118:121]
	v_mfma_f32_16x16x32_bf16 v[118:121], v[184:187], v[200:203], v[118:121]
	v_mfma_f32_16x16x32_bf16 v[102:105], v[180:183], v[204:207], v[102:105]
	v_mfma_f32_16x16x32_bf16 v[102:105], v[184:187], v[208:211], v[102:105]
	v_mfma_f32_16x16x32_bf16 v[86:89], v[180:183], v[212:215], v[86:89]
	v_mfma_f32_16x16x32_bf16 v[86:89], v[184:187], v[216:219], v[86:89]
	v_mfma_f32_16x16x32_bf16 v[70:73], v[180:183], v[220:223], v[70:73]
	v_mfma_f32_16x16x32_bf16 v[70:73], v[184:187], v[224:227], v[70:73]
	v_mfma_f32_16x16x32_bf16 v[122:125], v[172:175], v[196:199], v[122:125]
	v_mfma_f32_16x16x32_bf16 v[122:125], v[176:179], v[200:203], v[122:125]
	v_mfma_f32_16x16x32_bf16 v[106:109], v[172:175], v[204:207], v[106:109]
	v_mfma_f32_16x16x32_bf16 v[106:109], v[176:179], v[208:211], v[106:109]
	v_mfma_f32_16x16x32_bf16 v[90:93], v[172:175], v[212:215], v[90:93]
	v_mfma_f32_16x16x32_bf16 v[90:93], v[176:179], v[216:219], v[90:93]
	v_mfma_f32_16x16x32_bf16 v[74:77], v[172:175], v[220:223], v[74:77]
	v_mfma_f32_16x16x32_bf16 v[74:77], v[176:179], v[224:227], v[74:77]
	v_mfma_f32_16x16x32_bf16 v[114:117], v[188:191], v[196:199], v[114:117]
	v_mfma_f32_16x16x32_bf16 v[114:117], v[192:195], v[200:203], v[114:117]
	v_mfma_f32_16x16x32_bf16 v[98:101], v[188:191], v[204:207], v[98:101]
	v_mfma_f32_16x16x32_bf16 v[98:101], v[192:195], v[208:211], v[98:101]
	v_mfma_f32_16x16x32_bf16 v[82:85], v[188:191], v[212:215], v[82:85]
	v_mfma_f32_16x16x32_bf16 v[82:85], v[192:195], v[216:219], v[82:85]
	v_mfma_f32_16x16x32_bf16 v[66:69], v[188:191], v[220:223], v[66:69]
	v_mfma_f32_16x16x32_bf16 v[66:69], v[192:195], v[224:227], v[66:69]
	s_barrier
	s_add_i32 s60, s45, s38
	v_lshl_add_u64 v[146:147], s[28:29], 0, v[132:133]
	s_mov_b32 m0, s60
	ds_read_b128 v[196:199], v160 offset:16384
	ds_read_b128 v[200:203], v160 offset:17408
	ds_read_b128 v[204:207], v160 offset:18432
	ds_read_b128 v[208:211], v160 offset:19456
	ds_read_b128 v[212:215], v160 offset:20480
	ds_read_b128 v[216:219], v160 offset:21504
	ds_read_b128 v[220:223], v160 offset:22528
	ds_read_b128 v[224:227], v160 offset:23552
	global_load_lds_dwordx4 v[146:147], off
	s_add_i32 m0, s60, 0x2000
	s_add_u32 s60, s28, 0x100000
	v_lshl_add_u64 v[228:229], s[28:29], 0, v[136:137]
	s_addc_u32 s61, s29, 0
	s_add_i32 s62, s46, s38
	global_load_lds_dwordx4 v[228:229], off
	v_lshl_add_u64 v[230:231], s[60:61], 0, v[132:133]
	s_mov_b32 m0, s62
	v_lshl_add_u64 v[232:233], s[30:31], 0, v[134:135]
	global_load_lds_dwordx4 v[230:231], off
	v_lshl_add_u64 v[230:231], s[60:61], 0, v[136:137]
	s_add_i32 m0, s62, 0x2000
	s_nop 0
	global_load_lds_dwordx4 v[230:231], off
	v_lshl_add_u64 v[230:231], s[30:31], 0, v[130:131]
	s_mov_b32 m0, s25
	s_nop 0
	global_load_lds_dwordx4 v[230:231], off
	s_mov_b32 m0, s39
	s_nop 0
	global_load_lds_dwordx4 v[232:233], off
	s_waitcnt vmcnt(8)
	s_waitcnt lgkmcnt(0)
	s_barrier
	s_waitcnt lgkmcnt(0)
	v_mfma_f32_16x16x32_bf16 v[62:65], v[164:167], v[196:199], v[62:65]
	v_mfma_f32_16x16x32_bf16 v[62:65], v[168:171], v[200:203], v[62:65]
	v_mfma_f32_16x16x32_bf16 v[46:49], v[164:167], v[204:207], v[46:49]
	v_mfma_f32_16x16x32_bf16 v[46:49], v[168:171], v[208:211], v[46:49]
	v_mfma_f32_16x16x32_bf16 v[30:33], v[164:167], v[212:215], v[30:33]
	v_mfma_f32_16x16x32_bf16 v[30:33], v[168:171], v[216:219], v[30:33]
	v_mfma_f32_16x16x32_bf16 v[14:17], v[164:167], v[220:223], v[14:17]
	v_mfma_f32_16x16x32_bf16 v[14:17], v[168:171], v[224:227], v[14:17]
	v_mfma_f32_16x16x32_bf16 v[54:57], v[180:183], v[196:199], v[54:57]
	v_mfma_f32_16x16x32_bf16 v[54:57], v[184:187], v[200:203], v[54:57]
	v_mfma_f32_16x16x32_bf16 v[38:41], v[180:183], v[204:207], v[38:41]
	v_mfma_f32_16x16x32_bf16 v[38:41], v[184:187], v[208:211], v[38:41]
	v_mfma_f32_16x16x32_bf16 v[22:25], v[180:183], v[212:215], v[22:25]
	v_mfma_f32_16x16x32_bf16 v[22:25], v[184:187], v[216:219], v[22:25]
	v_mfma_f32_16x16x32_bf16 v[6:9], v[180:183], v[220:223], v[6:9]
	v_mfma_f32_16x16x32_bf16 v[6:9], v[184:187], v[224:227], v[6:9]
	v_mfma_f32_16x16x32_bf16 v[58:61], v[172:175], v[196:199], v[58:61]
	v_mfma_f32_16x16x32_bf16 v[58:61], v[176:179], v[200:203], v[58:61]
	v_mfma_f32_16x16x32_bf16 v[42:45], v[172:175], v[204:207], v[42:45]
	v_mfma_f32_16x16x32_bf16 v[42:45], v[176:179], v[208:211], v[42:45]
	v_mfma_f32_16x16x32_bf16 v[26:29], v[172:175], v[212:215], v[26:29]
	v_mfma_f32_16x16x32_bf16 v[26:29], v[176:179], v[216:219], v[26:29]
	v_mfma_f32_16x16x32_bf16 v[10:13], v[172:175], v[220:223], v[10:13]
	v_mfma_f32_16x16x32_bf16 v[10:13], v[176:179], v[224:227], v[10:13]
	v_mfma_f32_16x16x32_bf16 v[50:53], v[188:191], v[196:199], v[50:53]
	v_mfma_f32_16x16x32_bf16 v[50:53], v[192:195], v[200:203], v[50:53]
	v_mfma_f32_16x16x32_bf16 v[34:37], v[188:191], v[204:207], v[34:37]
	v_mfma_f32_16x16x32_bf16 v[34:37], v[192:195], v[208:211], v[34:37]
	v_mfma_f32_16x16x32_bf16 v[18:21], v[188:191], v[212:215], v[18:21]
	v_mfma_f32_16x16x32_bf16 v[18:21], v[192:195], v[216:219], v[18:21]
	v_mfma_f32_16x16x32_bf16 v[2:5], v[188:191], v[220:223], v[2:5]
	v_mfma_f32_16x16x32_bf16 v[2:5], v[192:195], v[224:227], v[2:5]
	s_barrier
	s_add_i32 s60, 0, 0x18000
	v_add_u32_e32 v161, s60, v156
	s_add_i32 s61, 0, 0x1c000
	ds_read_b128 v[164:167], v161
	ds_read_b128 v[168:171], v161 offset:1024
	ds_read_b128 v[172:175], v161 offset:2048
	ds_read_b128 v[176:179], v161 offset:3072
	v_add_u32_e32 v161, s61, v156
	ds_read_b128 v[180:183], v161
	ds_read_b128 v[184:187], v161 offset:1024
	ds_read_b128 v[188:191], v161 offset:2048
	ds_read_b128 v[192:195], v161 offset:3072
	s_add_u32 s30, s30, 0x100000
	s_addc_u32 s31, s31, 0
	s_mov_b32 m0, s40
	v_lshl_add_u64 v[234:235], s[30:31], 0, v[130:131]
	ds_read_b128 v[196:199], v160 offset:32768
	ds_read_b128 v[200:203], v160 offset:33792
	ds_read_b128 v[204:207], v160 offset:34816
	ds_read_b128 v[208:211], v160 offset:35840
	ds_read_b128 v[212:215], v160 offset:36864
	ds_read_b128 v[216:219], v160 offset:37888
	ds_read_b128 v[220:223], v160 offset:38912
	ds_read_b128 v[224:227], v160 offset:39936
	global_load_lds_dwordx4 v[234:235], off
	v_lshl_add_u64 v[234:235], s[30:31], 0, v[134:135]
	s_mov_b32 m0, s41
	s_nop 0
	global_load_lds_dwordx4 v[234:235], off
	s_waitcnt vmcnt(8)
	s_waitcnt lgkmcnt(0)
	s_barrier
	s_waitcnt lgkmcnt(0)
	v_mfma_f32_16x16x32_bf16 v[126:129], v[164:167], v[196:199], v[126:129]
	v_mfma_f32_16x16x32_bf16 v[126:129], v[168:171], v[200:203], v[126:129]
	v_mfma_f32_16x16x32_bf16 v[110:113], v[164:167], v[204:207], v[110:113]
	v_mfma_f32_16x16x32_bf16 v[110:113], v[168:171], v[208:211], v[110:113]
	v_mfma_f32_16x16x32_bf16 v[94:97], v[164:167], v[212:215], v[94:97]
	v_mfma_f32_16x16x32_bf16 v[94:97], v[168:171], v[216:219], v[94:97]
	v_mfma_f32_16x16x32_bf16 v[78:81], v[164:167], v[220:223], v[78:81]
	v_mfma_f32_16x16x32_bf16 v[78:81], v[168:171], v[224:227], v[78:81]
	v_mfma_f32_16x16x32_bf16 v[118:121], v[180:183], v[196:199], v[118:121]
	v_mfma_f32_16x16x32_bf16 v[118:121], v[184:187], v[200:203], v[118:121]
	v_mfma_f32_16x16x32_bf16 v[102:105], v[180:183], v[204:207], v[102:105]
	v_mfma_f32_16x16x32_bf16 v[102:105], v[184:187], v[208:211], v[102:105]
	v_mfma_f32_16x16x32_bf16 v[86:89], v[180:183], v[212:215], v[86:89]
	v_mfma_f32_16x16x32_bf16 v[86:89], v[184:187], v[216:219], v[86:89]
	v_mfma_f32_16x16x32_bf16 v[70:73], v[180:183], v[220:223], v[70:73]
	v_mfma_f32_16x16x32_bf16 v[70:73], v[184:187], v[224:227], v[70:73]
	v_mfma_f32_16x16x32_bf16 v[122:125], v[172:175], v[196:199], v[122:125]
	v_mfma_f32_16x16x32_bf16 v[122:125], v[176:179], v[200:203], v[122:125]
	v_mfma_f32_16x16x32_bf16 v[106:109], v[172:175], v[204:207], v[106:109]
	v_mfma_f32_16x16x32_bf16 v[106:109], v[176:179], v[208:211], v[106:109]
	v_mfma_f32_16x16x32_bf16 v[90:93], v[172:175], v[212:215], v[90:93]
	v_mfma_f32_16x16x32_bf16 v[90:93], v[176:179], v[216:219], v[90:93]
	v_mfma_f32_16x16x32_bf16 v[74:77], v[172:175], v[220:223], v[74:77]
	v_mfma_f32_16x16x32_bf16 v[74:77], v[176:179], v[224:227], v[74:77]
	v_mfma_f32_16x16x32_bf16 v[114:117], v[188:191], v[196:199], v[114:117]
	v_mfma_f32_16x16x32_bf16 v[114:117], v[192:195], v[200:203], v[114:117]
	v_mfma_f32_16x16x32_bf16 v[98:101], v[188:191], v[204:207], v[98:101]
	v_mfma_f32_16x16x32_bf16 v[98:101], v[192:195], v[208:211], v[98:101]
	v_mfma_f32_16x16x32_bf16 v[82:85], v[188:191], v[212:215], v[82:85]
	v_mfma_f32_16x16x32_bf16 v[82:85], v[192:195], v[216:219], v[82:85]
	v_mfma_f32_16x16x32_bf16 v[66:69], v[188:191], v[220:223], v[66:69]
	v_mfma_f32_16x16x32_bf16 v[66:69], v[192:195], v[224:227], v[66:69]
	s_barrier
	s_add_i32 s30, s60, s38
	v_lshl_add_u64 v[146:147], v[146:147], 0, s[12:13]
	s_mov_b32 m0, s30
	ds_read_b128 v[196:199], v160 offset:49152
	ds_read_b128 v[200:203], v160 offset:50176
	ds_read_b128 v[204:207], v160 offset:51200
	ds_read_b128 v[208:211], v160 offset:52224
	ds_read_b128 v[212:215], v160 offset:53248
	ds_read_b128 v[216:219], v160 offset:54272
	ds_read_b128 v[220:223], v160 offset:55296
	ds_read_b128 v[224:227], v160 offset:56320
	global_load_lds_dwordx4 v[146:147], off
	s_add_i32 m0, s30, 0x2000
	s_add_u32 s28, s28, 0x100080
	v_lshl_add_u64 v[146:147], v[228:229], 0, s[12:13]
	s_addc_u32 s29, s29, 0
	s_add_i32 s30, s61, s38
	global_load_lds_dwordx4 v[146:147], off
	v_lshl_add_u64 v[146:147], s[28:29], 0, v[132:133]
	s_mov_b32 m0, s30
	s_nop 0
	global_load_lds_dwordx4 v[146:147], off
	v_lshl_add_u64 v[146:147], s[28:29], 0, v[136:137]
	s_add_i32 m0, s30, 0x2000
	s_nop 0
	global_load_lds_dwordx4 v[146:147], off
	v_lshl_add_u64 v[146:147], v[230:231], 0, s[12:13]
	s_mov_b32 m0, s42
	s_nop 0
	global_load_lds_dwordx4 v[146:147], off
	v_lshl_add_u64 v[146:147], v[232:233], 0, s[12:13]
	s_mov_b32 m0, s43
	s_nop 0
	global_load_lds_dwordx4 v[146:147], off
	s_waitcnt vmcnt(8)
	s_waitcnt lgkmcnt(0)
	s_barrier
	s_waitcnt lgkmcnt(0)
	v_mfma_f32_16x16x32_bf16 v[62:65], v[164:167], v[196:199], v[62:65]
	v_mfma_f32_16x16x32_bf16 v[62:65], v[168:171], v[200:203], v[62:65]
	v_mfma_f32_16x16x32_bf16 v[46:49], v[164:167], v[204:207], v[46:49]
	v_mfma_f32_16x16x32_bf16 v[46:49], v[168:171], v[208:211], v[46:49]
	v_mfma_f32_16x16x32_bf16 v[30:33], v[164:167], v[212:215], v[30:33]
	v_mfma_f32_16x16x32_bf16 v[30:33], v[168:171], v[216:219], v[30:33]
	v_mfma_f32_16x16x32_bf16 v[14:17], v[164:167], v[220:223], v[14:17]
	v_mfma_f32_16x16x32_bf16 v[14:17], v[168:171], v[224:227], v[14:17]
	v_mfma_f32_16x16x32_bf16 v[54:57], v[180:183], v[196:199], v[54:57]
	v_mfma_f32_16x16x32_bf16 v[54:57], v[184:187], v[200:203], v[54:57]
	v_mfma_f32_16x16x32_bf16 v[38:41], v[180:183], v[204:207], v[38:41]
	v_mfma_f32_16x16x32_bf16 v[38:41], v[184:187], v[208:211], v[38:41]
	v_mfma_f32_16x16x32_bf16 v[22:25], v[180:183], v[212:215], v[22:25]
	v_mfma_f32_16x16x32_bf16 v[22:25], v[184:187], v[216:219], v[22:25]
	v_mfma_f32_16x16x32_bf16 v[6:9], v[180:183], v[220:223], v[6:9]
	v_mfma_f32_16x16x32_bf16 v[6:9], v[184:187], v[224:227], v[6:9]
	v_mfma_f32_16x16x32_bf16 v[58:61], v[172:175], v[196:199], v[58:61]
	v_mfma_f32_16x16x32_bf16 v[58:61], v[176:179], v[200:203], v[58:61]
	v_mfma_f32_16x16x32_bf16 v[42:45], v[172:175], v[204:207], v[42:45]
	v_mfma_f32_16x16x32_bf16 v[42:45], v[176:179], v[208:211], v[42:45]
	v_mfma_f32_16x16x32_bf16 v[26:29], v[172:175], v[212:215], v[26:29]
	v_mfma_f32_16x16x32_bf16 v[26:29], v[176:179], v[216:219], v[26:29]
	v_mfma_f32_16x16x32_bf16 v[10:13], v[172:175], v[220:223], v[10:13]
	v_mfma_f32_16x16x32_bf16 v[10:13], v[176:179], v[224:227], v[10:13]
	v_mfma_f32_16x16x32_bf16 v[50:53], v[188:191], v[196:199], v[50:53]
	v_mfma_f32_16x16x32_bf16 v[50:53], v[192:195], v[200:203], v[50:53]
	v_mfma_f32_16x16x32_bf16 v[34:37], v[188:191], v[204:207], v[34:37]
	v_mfma_f32_16x16x32_bf16 v[34:37], v[192:195], v[208:211], v[34:37]
	v_mfma_f32_16x16x32_bf16 v[18:21], v[188:191], v[212:215], v[18:21]
	v_mfma_f32_16x16x32_bf16 v[18:21], v[192:195], v[216:219], v[18:21]
	v_mfma_f32_16x16x32_bf16 v[2:5], v[188:191], v[220:223], v[2:5]
	v_mfma_f32_16x16x32_bf16 v[2:5], v[192:195], v[224:227], v[2:5]
	s_barrier
	s_add_i32 s59, s59, 2
	s_add_u32 s26, s26, 0x100
	s_addc_u32 s27, s27, 0
	s_add_u32 s57, s57, 0x100
	s_addc_u32 s58, s58, 0
	s_cmp_gt_u32 s59, 61
	s_cbranch_scc0 .LBB0_916
	s_and_b64 vcc, exec, s[14:15]
	s_cbranch_vccz .LBB0_919
	s_barrier

.LBB0_948:
	v_add_u32_e32 v147, s63, v161
	ds_read_b128 v[168:171], v147
	ds_read_b128 v[172:175], v147 offset:1024
	ds_read_b128 v[176:179], v147 offset:2048
	ds_read_b128 v[180:183], v147 offset:3072
	v_add_u32_e32 v147, s64, v161
	ds_read_b128 v[184:187], v147
	ds_read_b128 v[188:191], v147 offset:1024
	ds_read_b128 v[192:195], v147 offset:2048
	ds_read_b128 v[196:199], v147 offset:3072
	s_cmp_eq_u32 s46, 60
	v_lshl_add_u64 v[200:201], v[156:157], 0, s[34:35]
	s_cselect_b64 vcc, -1, 0
	v_cndmask_b32_e32 v233, v201, v1, vcc
	v_cndmask_b32_e32 v232, v200, v152, vcc
	v_cndmask_b32_e32 v235, v159, v145, vcc
	v_cndmask_b32_e32 v234, v158, v154, vcc
	v_lshl_add_u64 v[236:237], v[156:157], 0, v[138:139]
	s_add_i32 m0, s56, 0xc000
	ds_read_b128 v[200:203], v164
	ds_read_b128 v[204:207], v164 offset:1024
	ds_read_b128 v[208:211], v164 offset:2048
	ds_read_b128 v[212:215], v164 offset:3072
	ds_read_b128 v[216:219], v164 offset:4096
	ds_read_b128 v[220:223], v164 offset:5120
	ds_read_b128 v[224:227], v164 offset:6144
	ds_read_b128 v[228:231], v164 offset:7168
	global_load_lds_dwordx4 v[236:237], off
	v_lshl_add_u64 v[236:237], v[156:157], 0, v[140:141]
	s_add_i32 m0, s56, 0xe000
	s_nop 0
	global_load_lds_dwordx4 v[236:237], off
	s_waitcnt vmcnt(8)
	s_waitcnt lgkmcnt(0)
	s_barrier
	s_waitcnt lgkmcnt(0)
	v_mfma_f32_16x16x32_bf16 v[126:129], v[168:171], v[200:203], v[126:129]
	v_mfma_f32_16x16x32_bf16 v[126:129], v[172:175], v[204:207], v[126:129]
	v_mfma_f32_16x16x32_bf16 v[110:113], v[168:171], v[208:211], v[110:113]
	v_mfma_f32_16x16x32_bf16 v[110:113], v[172:175], v[212:215], v[110:113]
	v_mfma_f32_16x16x32_bf16 v[94:97], v[168:171], v[216:219], v[94:97]
	v_mfma_f32_16x16x32_bf16 v[94:97], v[172:175], v[220:223], v[94:97]
	v_mfma_f32_16x16x32_bf16 v[78:81], v[168:171], v[224:227], v[78:81]
	v_mfma_f32_16x16x32_bf16 v[78:81], v[172:175], v[228:231], v[78:81]
	v_mfma_f32_16x16x32_bf16 v[118:121], v[184:187], v[200:203], v[118:121]
	v_mfma_f32_16x16x32_bf16 v[118:121], v[188:191], v[204:207], v[118:121]
	v_mfma_f32_16x16x32_bf16 v[102:105], v[184:187], v[208:211], v[102:105]
	v_mfma_f32_16x16x32_bf16 v[102:105], v[188:191], v[212:215], v[102:105]
	v_mfma_f32_16x16x32_bf16 v[86:89], v[184:187], v[216:219], v[86:89]
	v_mfma_f32_16x16x32_bf16 v[86:89], v[188:191], v[220:223], v[86:89]
	v_mfma_f32_16x16x32_bf16 v[70:73], v[184:187], v[224:227], v[70:73]
	v_mfma_f32_16x16x32_bf16 v[70:73], v[188:191], v[228:231], v[70:73]
	v_mfma_f32_16x16x32_bf16 v[122:125], v[176:179], v[200:203], v[122:125]
	v_mfma_f32_16x16x32_bf16 v[122:125], v[180:183], v[204:207], v[122:125]
	v_mfma_f32_16x16x32_bf16 v[106:109], v[176:179], v[208:211], v[106:109]
	v_mfma_f32_16x16x32_bf16 v[106:109], v[180:183], v[212:215], v[106:109]
	v_mfma_f32_16x16x32_bf16 v[90:93], v[176:179], v[216:219], v[90:93]
	v_mfma_f32_16x16x32_bf16 v[90:93], v[180:183], v[220:223], v[90:93]
	v_mfma_f32_16x16x32_bf16 v[74:77], v[176:179], v[224:227], v[74:77]
	v_mfma_f32_16x16x32_bf16 v[74:77], v[180:183], v[228:231], v[74:77]
	v_mfma_f32_16x16x32_bf16 v[114:117], v[192:195], v[200:203], v[114:117]
	v_mfma_f32_16x16x32_bf16 v[114:117], v[196:199], v[204:207], v[114:117]
	v_mfma_f32_16x16x32_bf16 v[98:101], v[192:195], v[208:211], v[98:101]
	v_mfma_f32_16x16x32_bf16 v[98:101], v[196:199], v[212:215], v[98:101]
	v_mfma_f32_16x16x32_bf16 v[82:85], v[192:195], v[216:219], v[82:85]
	v_mfma_f32_16x16x32_bf16 v[82:85], v[196:199], v[220:223], v[82:85]
	v_mfma_f32_16x16x32_bf16 v[66:69], v[192:195], v[224:227], v[66:69]
	v_mfma_f32_16x16x32_bf16 v[66:69], v[196:199], v[228:231], v[66:69]
	s_barrier
	s_add_i32 s47, s63, s53
	v_lshl_add_u64 v[236:237], v[234:235], 0, v[132:133]
	s_mov_b32 m0, s47
	ds_read_b128 v[200:203], v164 offset:16384
	ds_read_b128 v[204:207], v164 offset:17408
	ds_read_b128 v[208:211], v164 offset:18432
	ds_read_b128 v[212:215], v164 offset:19456
	ds_read_b128 v[216:219], v164 offset:20480
	ds_read_b128 v[220:223], v164 offset:21504
	ds_read_b128 v[224:227], v164 offset:22528
	ds_read_b128 v[228:231], v164 offset:23552
	global_load_lds_dwordx4 v[236:237], off
	v_lshl_add_u64 v[238:239], v[234:235], 0, v[136:137]
	s_add_i32 m0, s47, 0x2000
	v_lshl_add_u64 v[240:241], v[234:235], 0, s[10:11]
	s_add_i32 s47, s64, s53
	global_load_lds_dwordx4 v[238:239], off
	v_lshl_add_u64 v[242:243], v[240:241], 0, v[132:133]
	s_mov_b32 m0, s47
	v_lshl_add_u64 v[240:241], v[240:241], 0, v[136:137]
	global_load_lds_dwordx4 v[242:243], off
	s_add_i32 m0, s47, 0x2000
	v_lshl_add_u64 v[242:243], v[232:233], 0, v[134:135]
	global_load_lds_dwordx4 v[240:241], off
	v_lshl_add_u64 v[240:241], v[232:233], 0, v[130:131]
	s_mov_b32 m0, s56
	s_nop 0
	global_load_lds_dwordx4 v[240:241], off
	s_mov_b32 m0, s57
	s_nop 0
	global_load_lds_dwordx4 v[242:243], off
	s_waitcnt vmcnt(8)
	s_waitcnt lgkmcnt(0)
	s_barrier
	s_waitcnt lgkmcnt(0)
	v_mfma_f32_16x16x32_bf16 v[62:65], v[168:171], v[200:203], v[62:65]
	v_mfma_f32_16x16x32_bf16 v[62:65], v[172:175], v[204:207], v[62:65]
	v_mfma_f32_16x16x32_bf16 v[46:49], v[168:171], v[208:211], v[46:49]
	v_mfma_f32_16x16x32_bf16 v[46:49], v[172:175], v[212:215], v[46:49]
	v_mfma_f32_16x16x32_bf16 v[30:33], v[168:171], v[216:219], v[30:33]
	v_mfma_f32_16x16x32_bf16 v[30:33], v[172:175], v[220:223], v[30:33]
	v_mfma_f32_16x16x32_bf16 v[14:17], v[168:171], v[224:227], v[14:17]
	v_mfma_f32_16x16x32_bf16 v[14:17], v[172:175], v[228:231], v[14:17]
	v_mfma_f32_16x16x32_bf16 v[54:57], v[184:187], v[200:203], v[54:57]
	v_mfma_f32_16x16x32_bf16 v[54:57], v[188:191], v[204:207], v[54:57]
	v_mfma_f32_16x16x32_bf16 v[38:41], v[184:187], v[208:211], v[38:41]
	v_mfma_f32_16x16x32_bf16 v[38:41], v[188:191], v[212:215], v[38:41]
	v_mfma_f32_16x16x32_bf16 v[22:25], v[184:187], v[216:219], v[22:25]
	v_mfma_f32_16x16x32_bf16 v[22:25], v[188:191], v[220:223], v[22:25]
	v_mfma_f32_16x16x32_bf16 v[6:9], v[184:187], v[224:227], v[6:9]
	v_mfma_f32_16x16x32_bf16 v[6:9], v[188:191], v[228:231], v[6:9]
	v_mfma_f32_16x16x32_bf16 v[58:61], v[176:179], v[200:203], v[58:61]
	v_mfma_f32_16x16x32_bf16 v[58:61], v[180:183], v[204:207], v[58:61]
	v_mfma_f32_16x16x32_bf16 v[42:45], v[176:179], v[208:211], v[42:45]
	v_mfma_f32_16x16x32_bf16 v[42:45], v[180:183], v[212:215], v[42:45]
	v_mfma_f32_16x16x32_bf16 v[26:29], v[176:179], v[216:219], v[26:29]
	v_mfma_f32_16x16x32_bf16 v[26:29], v[180:183], v[220:223], v[26:29]
	v_mfma_f32_16x16x32_bf16 v[10:13], v[176:179], v[224:227], v[10:13]
	v_mfma_f32_16x16x32_bf16 v[10:13], v[180:183], v[228:231], v[10:13]
	v_mfma_f32_16x16x32_bf16 v[50:53], v[192:195], v[200:203], v[50:53]
	v_mfma_f32_16x16x32_bf16 v[50:53], v[196:199], v[204:207], v[50:53]
	v_mfma_f32_16x16x32_bf16 v[34:37], v[192:195], v[208:211], v[34:37]
	v_mfma_f32_16x16x32_bf16 v[34:37], v[196:199], v[212:215], v[34:37]
	v_mfma_f32_16x16x32_bf16 v[18:21], v[192:195], v[216:219], v[18:21]
	v_mfma_f32_16x16x32_bf16 v[18:21], v[196:199], v[220:223], v[18:21]
	v_mfma_f32_16x16x32_bf16 v[2:5], v[192:195], v[224:227], v[2:5]
	v_mfma_f32_16x16x32_bf16 v[2:5], v[196:199], v[228:231], v[2:5]
	s_barrier
	s_add_i32 s47, 0, 0x18000
	v_add_u32_e32 v147, s47, v161
	s_add_i32 s48, 0, 0x1c000
	ds_read_b128 v[168:171], v147
	ds_read_b128 v[172:175], v147 offset:1024
	ds_read_b128 v[176:179], v147 offset:2048
	ds_read_b128 v[180:183], v147 offset:3072
	v_add_u32_e32 v147, s48, v161
	ds_read_b128 v[184:187], v147
	ds_read_b128 v[188:191], v147 offset:1024
	ds_read_b128 v[192:195], v147 offset:2048
	ds_read_b128 v[196:199], v147 offset:3072
	v_lshl_add_u64 v[232:233], v[232:233], 0, s[10:11]
	s_mov_b32 m0, s58
	v_lshl_add_u64 v[244:245], v[232:233], 0, v[130:131]
	ds_read_b128 v[200:203], v164 offset:32768
	ds_read_b128 v[204:207], v164 offset:33792
	ds_read_b128 v[208:211], v164 offset:34816
	ds_read_b128 v[212:215], v164 offset:35840
	ds_read_b128 v[216:219], v164 offset:36864
	ds_read_b128 v[220:223], v164 offset:37888
	ds_read_b128 v[224:227], v164 offset:38912
	ds_read_b128 v[228:231], v164 offset:39936
	global_load_lds_dwordx4 v[244:245], off
	v_lshl_add_u64 v[232:233], v[232:233], 0, v[134:135]
	s_mov_b32 m0, s59
	s_nop 0
	global_load_lds_dwordx4 v[232:233], off
	s_waitcnt vmcnt(8)
	s_waitcnt lgkmcnt(0)
	s_barrier
	s_waitcnt lgkmcnt(0)
	v_mfma_f32_16x16x32_bf16 v[126:129], v[168:171], v[200:203], v[126:129]
	v_mfma_f32_16x16x32_bf16 v[126:129], v[172:175], v[204:207], v[126:129]
	v_mfma_f32_16x16x32_bf16 v[110:113], v[168:171], v[208:211], v[110:113]
	v_mfma_f32_16x16x32_bf16 v[110:113], v[172:175], v[212:215], v[110:113]
	v_mfma_f32_16x16x32_bf16 v[94:97], v[168:171], v[216:219], v[94:97]
	v_mfma_f32_16x16x32_bf16 v[94:97], v[172:175], v[220:223], v[94:97]
	v_mfma_f32_16x16x32_bf16 v[78:81], v[168:171], v[224:227], v[78:81]
	v_mfma_f32_16x16x32_bf16 v[78:81], v[172:175], v[228:231], v[78:81]
	v_mfma_f32_16x16x32_bf16 v[118:121], v[184:187], v[200:203], v[118:121]
	v_mfma_f32_16x16x32_bf16 v[118:121], v[188:191], v[204:207], v[118:121]
	v_mfma_f32_16x16x32_bf16 v[102:105], v[184:187], v[208:211], v[102:105]
	v_mfma_f32_16x16x32_bf16 v[102:105], v[188:191], v[212:215], v[102:105]
	v_mfma_f32_16x16x32_bf16 v[86:89], v[184:187], v[216:219], v[86:89]
	v_mfma_f32_16x16x32_bf16 v[86:89], v[188:191], v[220:223], v[86:89]
	v_mfma_f32_16x16x32_bf16 v[70:73], v[184:187], v[224:227], v[70:73]
	v_mfma_f32_16x16x32_bf16 v[70:73], v[188:191], v[228:231], v[70:73]
	v_mfma_f32_16x16x32_bf16 v[122:125], v[176:179], v[200:203], v[122:125]
	v_mfma_f32_16x16x32_bf16 v[122:125], v[180:183], v[204:207], v[122:125]
	v_mfma_f32_16x16x32_bf16 v[106:109], v[176:179], v[208:211], v[106:109]
	v_mfma_f32_16x16x32_bf16 v[106:109], v[180:183], v[212:215], v[106:109]
	v_mfma_f32_16x16x32_bf16 v[90:93], v[176:179], v[216:219], v[90:93]
	v_mfma_f32_16x16x32_bf16 v[90:93], v[180:183], v[220:223], v[90:93]
	v_mfma_f32_16x16x32_bf16 v[74:77], v[176:179], v[224:227], v[74:77]
	v_mfma_f32_16x16x32_bf16 v[74:77], v[180:183], v[228:231], v[74:77]
	v_mfma_f32_16x16x32_bf16 v[114:117], v[192:195], v[200:203], v[114:117]
	v_mfma_f32_16x16x32_bf16 v[114:117], v[196:199], v[204:207], v[114:117]
	v_mfma_f32_16x16x32_bf16 v[98:101], v[192:195], v[208:211], v[98:101]
	v_mfma_f32_16x16x32_bf16 v[98:101], v[196:199], v[212:215], v[98:101]
	v_mfma_f32_16x16x32_bf16 v[82:85], v[192:195], v[216:219], v[82:85]
	v_mfma_f32_16x16x32_bf16 v[82:85], v[196:199], v[220:223], v[82:85]
	v_mfma_f32_16x16x32_bf16 v[66:69], v[192:195], v[224:227], v[66:69]
	v_mfma_f32_16x16x32_bf16 v[66:69], v[196:199], v[228:231], v[66:69]
	s_barrier
	s_add_i32 s47, s47, s53
	v_lshl_add_u64 v[232:233], v[236:237], 0, s[18:19]
	s_mov_b32 m0, s47
	ds_read_b128 v[200:203], v164 offset:49152
	ds_read_b128 v[204:207], v164 offset:50176
	ds_read_b128 v[208:211], v164 offset:51200
	ds_read_b128 v[212:215], v164 offset:52224
	ds_read_b128 v[216:219], v164 offset:53248
	ds_read_b128 v[220:223], v164 offset:54272
	ds_read_b128 v[224:227], v164 offset:55296
	ds_read_b128 v[228:231], v164 offset:56320
	global_load_lds_dwordx4 v[232:233], off
	v_lshl_add_u64 v[232:233], v[238:239], 0, s[18:19]
	s_add_i32 m0, s47, 0x2000
	s_add_i32 s47, s48, s53
	global_load_lds_dwordx4 v[232:233], off
	v_lshl_add_u64 v[232:233], v[234:235], 0, s[22:23]
	v_lshl_add_u64 v[234:235], v[232:233], 0, v[132:133]
	s_mov_b32 m0, s47
	v_lshl_add_u64 v[232:233], v[232:233], 0, v[136:137]
	global_load_lds_dwordx4 v[234:235], off
	s_add_i32 m0, s47, 0x2000
	s_nop 0
	global_load_lds_dwordx4 v[232:233], off
	v_lshl_add_u64 v[232:233], v[240:241], 0, s[18:19]
	s_mov_b32 m0, s61
	s_nop 0
	global_load_lds_dwordx4 v[232:233], off
	v_lshl_add_u64 v[232:233], v[242:243], 0, s[18:19]
	s_mov_b32 m0, s62
	s_nop 0
	global_load_lds_dwordx4 v[232:233], off
	s_waitcnt vmcnt(8)
	s_waitcnt lgkmcnt(0)
	s_barrier
	s_waitcnt lgkmcnt(0)
	v_mfma_f32_16x16x32_bf16 v[62:65], v[168:171], v[200:203], v[62:65]
	v_mfma_f32_16x16x32_bf16 v[62:65], v[172:175], v[204:207], v[62:65]
	v_mfma_f32_16x16x32_bf16 v[46:49], v[168:171], v[208:211], v[46:49]
	v_mfma_f32_16x16x32_bf16 v[46:49], v[172:175], v[212:215], v[46:49]
	v_mfma_f32_16x16x32_bf16 v[30:33], v[168:171], v[216:219], v[30:33]
	v_mfma_f32_16x16x32_bf16 v[30:33], v[172:175], v[220:223], v[30:33]
	v_mfma_f32_16x16x32_bf16 v[14:17], v[168:171], v[224:227], v[14:17]
	v_mfma_f32_16x16x32_bf16 v[14:17], v[172:175], v[228:231], v[14:17]
	v_mfma_f32_16x16x32_bf16 v[54:57], v[184:187], v[200:203], v[54:57]
	v_mfma_f32_16x16x32_bf16 v[54:57], v[188:191], v[204:207], v[54:57]
	v_mfma_f32_16x16x32_bf16 v[38:41], v[184:187], v[208:211], v[38:41]
	v_mfma_f32_16x16x32_bf16 v[38:41], v[188:191], v[212:215], v[38:41]
	v_mfma_f32_16x16x32_bf16 v[22:25], v[184:187], v[216:219], v[22:25]
	v_mfma_f32_16x16x32_bf16 v[22:25], v[188:191], v[220:223], v[22:25]
	v_mfma_f32_16x16x32_bf16 v[6:9], v[184:187], v[224:227], v[6:9]
	v_mfma_f32_16x16x32_bf16 v[6:9], v[188:191], v[228:231], v[6:9]
	v_mfma_f32_16x16x32_bf16 v[58:61], v[176:179], v[200:203], v[58:61]
	v_mfma_f32_16x16x32_bf16 v[58:61], v[180:183], v[204:207], v[58:61]
	v_mfma_f32_16x16x32_bf16 v[42:45], v[176:179], v[208:211], v[42:45]
	v_mfma_f32_16x16x32_bf16 v[42:45], v[180:183], v[212:215], v[42:45]
	v_mfma_f32_16x16x32_bf16 v[26:29], v[176:179], v[216:219], v[26:29]
	v_mfma_f32_16x16x32_bf16 v[26:29], v[180:183], v[220:223], v[26:29]
	v_mfma_f32_16x16x32_bf16 v[10:13], v[176:179], v[224:227], v[10:13]
	v_mfma_f32_16x16x32_bf16 v[10:13], v[180:183], v[228:231], v[10:13]
	v_mfma_f32_16x16x32_bf16 v[50:53], v[192:195], v[200:203], v[50:53]
	v_mfma_f32_16x16x32_bf16 v[50:53], v[196:199], v[204:207], v[50:53]
	v_mfma_f32_16x16x32_bf16 v[34:37], v[192:195], v[208:211], v[34:37]
	v_mfma_f32_16x16x32_bf16 v[34:37], v[196:199], v[212:215], v[34:37]
	v_mfma_f32_16x16x32_bf16 v[18:21], v[192:195], v[216:219], v[18:21]
	v_mfma_f32_16x16x32_bf16 v[18:21], v[196:199], v[220:223], v[18:21]
	v_mfma_f32_16x16x32_bf16 v[2:5], v[192:195], v[224:227], v[2:5]
	v_mfma_f32_16x16x32_bf16 v[2:5], v[196:199], v[228:231], v[2:5]
	s_barrier
	s_add_i32 s46, s46, 2
	v_lshl_add_u64 v[156:157], v[156:157], 0, s[30:31]
	s_cmp_gt_u32 s46, 61
	v_lshl_add_u64 v[158:159], v[158:159], 0, s[30:31]
	s_cbranch_scc0 .LBB0_948
	s_and_b64 vcc, exec, s[24:25]
	s_cbranch_vccz .LBB0_951
	s_barrier

.LBB0_1098:
	ds_read_b128 v[140:143], v165
	ds_read_b128 v[144:147], v165 offset:1024
	ds_read_b128 v[148:151], v165 offset:2048
	ds_read_b128 v[152:155], v165 offset:3072
	ds_read_b128 v[156:159], v166
	ds_read_b128 v[168:171], v166 offset:1024
	ds_read_b128 v[172:175], v166 offset:2048
	ds_read_b128 v[176:179], v166 offset:3072
	s_add_u32 s28, s26, 0xffe00080
	s_addc_u32 s29, s27, -1
	s_cmpk_eq_i32 s55, 0x7c
	s_cselect_b32 s31, s19, s29
	s_cselect_b32 s30, s51, s28
	s_cselect_b32 s29, s17, s54
	s_cselect_b32 s28, s52, s53
	v_lshl_add_u64 v[160:161], s[26:27], 0, v[132:133]
	s_add_i32 m0, s25, 0xc000
	ds_read_b128 v[180:183], v167
	ds_read_b128 v[184:187], v167 offset:1024
	ds_read_b128 v[188:191], v167 offset:2048
	ds_read_b128 v[192:195], v167 offset:3072
	ds_read_b128 v[196:199], v167 offset:4096
	ds_read_b128 v[200:203], v167 offset:5120
	ds_read_b128 v[204:207], v167 offset:6144
	ds_read_b128 v[208:211], v167 offset:7168
	global_load_lds_dwordx4 v[160:161], off
	v_lshl_add_u64 v[160:161], s[26:27], 0, v[134:135]
	s_add_i32 m0, s25, 0xe000
	s_nop 0
	global_load_lds_dwordx4 v[160:161], off
	s_waitcnt vmcnt(8)
	s_waitcnt lgkmcnt(0)
	s_barrier
	s_waitcnt lgkmcnt(0)
	v_mfma_f32_16x16x32_bf16 v[124:127], v[140:143], v[180:183], v[124:127]
	v_mfma_f32_16x16x32_bf16 v[124:127], v[144:147], v[184:187], v[124:127]
	v_mfma_f32_16x16x32_bf16 v[108:111], v[140:143], v[188:191], v[108:111]
	v_mfma_f32_16x16x32_bf16 v[108:111], v[144:147], v[192:195], v[108:111]
	v_mfma_f32_16x16x32_bf16 v[92:95], v[140:143], v[196:199], v[92:95]
	v_mfma_f32_16x16x32_bf16 v[92:95], v[144:147], v[200:203], v[92:95]
	v_mfma_f32_16x16x32_bf16 v[76:79], v[140:143], v[204:207], v[76:79]
	v_mfma_f32_16x16x32_bf16 v[76:79], v[144:147], v[208:211], v[76:79]
	v_mfma_f32_16x16x32_bf16 v[116:119], v[156:159], v[180:183], v[116:119]
	v_mfma_f32_16x16x32_bf16 v[116:119], v[168:171], v[184:187], v[116:119]
	v_mfma_f32_16x16x32_bf16 v[100:103], v[156:159], v[188:191], v[100:103]
	v_mfma_f32_16x16x32_bf16 v[100:103], v[168:171], v[192:195], v[100:103]
	v_mfma_f32_16x16x32_bf16 v[84:87], v[156:159], v[196:199], v[84:87]
	v_mfma_f32_16x16x32_bf16 v[84:87], v[168:171], v[200:203], v[84:87]
	v_mfma_f32_16x16x32_bf16 v[68:71], v[156:159], v[204:207], v[68:71]
	v_mfma_f32_16x16x32_bf16 v[68:71], v[168:171], v[208:211], v[68:71]
	v_mfma_f32_16x16x32_bf16 v[120:123], v[148:151], v[180:183], v[120:123]
	v_mfma_f32_16x16x32_bf16 v[120:123], v[152:155], v[184:187], v[120:123]
	v_mfma_f32_16x16x32_bf16 v[104:107], v[148:151], v[188:191], v[104:107]
	v_mfma_f32_16x16x32_bf16 v[104:107], v[152:155], v[192:195], v[104:107]
	v_mfma_f32_16x16x32_bf16 v[88:91], v[148:151], v[196:199], v[88:91]
	v_mfma_f32_16x16x32_bf16 v[88:91], v[152:155], v[200:203], v[88:91]
	v_mfma_f32_16x16x32_bf16 v[72:75], v[148:151], v[204:207], v[72:75]
	v_mfma_f32_16x16x32_bf16 v[72:75], v[152:155], v[208:211], v[72:75]
	v_mfma_f32_16x16x32_bf16 v[112:115], v[172:175], v[180:183], v[112:115]
	v_mfma_f32_16x16x32_bf16 v[112:115], v[176:179], v[184:187], v[112:115]
	v_mfma_f32_16x16x32_bf16 v[96:99], v[172:175], v[188:191], v[96:99]
	v_mfma_f32_16x16x32_bf16 v[96:99], v[176:179], v[192:195], v[96:99]
	v_mfma_f32_16x16x32_bf16 v[80:83], v[172:175], v[196:199], v[80:83]
	v_mfma_f32_16x16x32_bf16 v[80:83], v[176:179], v[200:203], v[80:83]
	v_mfma_f32_16x16x32_bf16 v[64:67], v[172:175], v[204:207], v[64:67]
	v_mfma_f32_16x16x32_bf16 v[64:67], v[176:179], v[208:211], v[64:67]
	s_barrier
	s_add_i32 s56, s48, s38
	v_lshl_add_u64 v[160:161], s[28:29], 0, v[128:129]
	s_mov_b32 m0, s56
	ds_read_b128 v[180:183], v167 offset:16384
	ds_read_b128 v[184:187], v167 offset:17408
	ds_read_b128 v[188:191], v167 offset:18432
	ds_read_b128 v[192:195], v167 offset:19456
	ds_read_b128 v[196:199], v167 offset:20480
	ds_read_b128 v[200:203], v167 offset:21504
	ds_read_b128 v[204:207], v167 offset:22528
	ds_read_b128 v[208:211], v167 offset:23552
	global_load_lds_dwordx4 v[160:161], off
	s_add_i32 m0, s56, 0x2000
	s_add_u32 s56, s28, 0x200000
	v_lshl_add_u64 v[212:213], s[28:29], 0, v[130:131]
	s_addc_u32 s57, s29, 0
	s_add_i32 s58, s49, s38
	global_load_lds_dwordx4 v[212:213], off
	v_lshl_add_u64 v[214:215], s[56:57], 0, v[128:129]
	s_mov_b32 m0, s58
	v_lshl_add_u64 v[216:217], s[30:31], 0, v[130:131]
	global_load_lds_dwordx4 v[214:215], off
	v_lshl_add_u64 v[214:215], s[56:57], 0, v[130:131]
	s_add_i32 m0, s58, 0x2000
	s_nop 0
	global_load_lds_dwordx4 v[214:215], off
	v_lshl_add_u64 v[214:215], s[30:31], 0, v[128:129]
	s_mov_b32 m0, s25
	s_nop 0
	global_load_lds_dwordx4 v[214:215], off
	s_mov_b32 m0, s40
	s_nop 0
	global_load_lds_dwordx4 v[216:217], off
	s_waitcnt vmcnt(8)
	s_waitcnt lgkmcnt(0)
	s_barrier
	s_waitcnt lgkmcnt(0)
	v_mfma_f32_16x16x32_bf16 v[60:63], v[140:143], v[180:183], v[60:63]
	v_mfma_f32_16x16x32_bf16 v[60:63], v[144:147], v[184:187], v[60:63]
	v_mfma_f32_16x16x32_bf16 v[44:47], v[140:143], v[188:191], v[44:47]
	v_mfma_f32_16x16x32_bf16 v[44:47], v[144:147], v[192:195], v[44:47]
	v_mfma_f32_16x16x32_bf16 v[28:31], v[140:143], v[196:199], v[28:31]
	v_mfma_f32_16x16x32_bf16 v[28:31], v[144:147], v[200:203], v[28:31]
	v_mfma_f32_16x16x32_bf16 v[16:19], v[140:143], v[204:207], v[16:19]
	v_mfma_f32_16x16x32_bf16 v[16:19], v[144:147], v[208:211], v[16:19]
	v_mfma_f32_16x16x32_bf16 v[52:55], v[156:159], v[180:183], v[52:55]
	v_mfma_f32_16x16x32_bf16 v[52:55], v[168:171], v[184:187], v[52:55]
	v_mfma_f32_16x16x32_bf16 v[36:39], v[156:159], v[188:191], v[36:39]
	v_mfma_f32_16x16x32_bf16 v[36:39], v[168:171], v[192:195], v[36:39]
	v_mfma_f32_16x16x32_bf16 v[20:23], v[156:159], v[196:199], v[20:23]
	v_mfma_f32_16x16x32_bf16 v[20:23], v[168:171], v[200:203], v[20:23]
	v_mfma_f32_16x16x32_bf16 v[4:7], v[156:159], v[204:207], v[4:7]
	v_mfma_f32_16x16x32_bf16 v[4:7], v[168:171], v[208:211], v[4:7]
	v_mfma_f32_16x16x32_bf16 v[56:59], v[148:151], v[180:183], v[56:59]
	v_mfma_f32_16x16x32_bf16 v[56:59], v[152:155], v[184:187], v[56:59]
	v_mfma_f32_16x16x32_bf16 v[40:43], v[148:151], v[188:191], v[40:43]
	v_mfma_f32_16x16x32_bf16 v[40:43], v[152:155], v[192:195], v[40:43]
	v_mfma_f32_16x16x32_bf16 v[24:27], v[148:151], v[196:199], v[24:27]
	v_mfma_f32_16x16x32_bf16 v[24:27], v[152:155], v[200:203], v[24:27]
	v_mfma_f32_16x16x32_bf16 v[8:11], v[148:151], v[204:207], v[8:11]
	v_mfma_f32_16x16x32_bf16 v[8:11], v[152:155], v[208:211], v[8:11]
	v_mfma_f32_16x16x32_bf16 v[48:51], v[172:175], v[180:183], v[48:51]
	v_mfma_f32_16x16x32_bf16 v[48:51], v[176:179], v[184:187], v[48:51]
	v_mfma_f32_16x16x32_bf16 v[32:35], v[172:175], v[188:191], v[32:35]
	v_mfma_f32_16x16x32_bf16 v[32:35], v[176:179], v[192:195], v[32:35]
	v_mfma_f32_16x16x32_bf16 v[12:15], v[172:175], v[196:199], v[12:15]
	v_mfma_f32_16x16x32_bf16 v[12:15], v[176:179], v[200:203], v[12:15]
	v_mfma_f32_16x16x32_bf16 v[0:3], v[172:175], v[204:207], v[0:3]
	v_mfma_f32_16x16x32_bf16 v[0:3], v[176:179], v[208:211], v[0:3]
	s_barrier
	s_add_i32 s56, 0, 0x18000
	s_add_i32 s57, 0, 0x1c000
	v_add_u32_e32 v152, s56, v163
	v_add_u32_e32 v176, s57, v163
	ds_read_b128 v[140:143], v152
	ds_read_b128 v[144:147], v152 offset:1024
	ds_read_b128 v[148:151], v152 offset:2048
	ds_read_b128 v[152:155], v152 offset:3072
	ds_read_b128 v[156:159], v176
	ds_read_b128 v[168:171], v176 offset:1024
	ds_read_b128 v[172:175], v176 offset:2048
	ds_read_b128 v[176:179], v176 offset:3072
	s_add_u32 s30, s30, 0x200000
	s_addc_u32 s31, s31, 0
	s_mov_b32 m0, s41
	v_lshl_add_u64 v[218:219], s[30:31], 0, v[128:129]
	ds_read_b128 v[180:183], v167 offset:32768
	ds_read_b128 v[184:187], v167 offset:33792
	ds_read_b128 v[188:191], v167 offset:34816
	ds_read_b128 v[192:195], v167 offset:35840
	ds_read_b128 v[196:199], v167 offset:36864
	ds_read_b128 v[200:203], v167 offset:37888
	ds_read_b128 v[204:207], v167 offset:38912
	ds_read_b128 v[208:211], v167 offset:39936
	global_load_lds_dwordx4 v[218:219], off
	v_lshl_add_u64 v[218:219], s[30:31], 0, v[130:131]
	s_mov_b32 m0, s42
	s_nop 0
	global_load_lds_dwordx4 v[218:219], off
	s_waitcnt vmcnt(8)
	s_waitcnt lgkmcnt(0)
	s_barrier
	s_waitcnt lgkmcnt(0)
	v_mfma_f32_16x16x32_bf16 v[124:127], v[140:143], v[180:183], v[124:127]
	v_mfma_f32_16x16x32_bf16 v[124:127], v[144:147], v[184:187], v[124:127]
	v_mfma_f32_16x16x32_bf16 v[108:111], v[140:143], v[188:191], v[108:111]
	v_mfma_f32_16x16x32_bf16 v[108:111], v[144:147], v[192:195], v[108:111]
	v_mfma_f32_16x16x32_bf16 v[92:95], v[140:143], v[196:199], v[92:95]
	v_mfma_f32_16x16x32_bf16 v[92:95], v[144:147], v[200:203], v[92:95]
	v_mfma_f32_16x16x32_bf16 v[76:79], v[140:143], v[204:207], v[76:79]
	v_mfma_f32_16x16x32_bf16 v[76:79], v[144:147], v[208:211], v[76:79]
	v_mfma_f32_16x16x32_bf16 v[116:119], v[156:159], v[180:183], v[116:119]
	v_mfma_f32_16x16x32_bf16 v[116:119], v[168:171], v[184:187], v[116:119]
	v_mfma_f32_16x16x32_bf16 v[100:103], v[156:159], v[188:191], v[100:103]
	v_mfma_f32_16x16x32_bf16 v[100:103], v[168:171], v[192:195], v[100:103]
	v_mfma_f32_16x16x32_bf16 v[84:87], v[156:159], v[196:199], v[84:87]
	v_mfma_f32_16x16x32_bf16 v[84:87], v[168:171], v[200:203], v[84:87]
	v_mfma_f32_16x16x32_bf16 v[68:71], v[156:159], v[204:207], v[68:71]
	v_mfma_f32_16x16x32_bf16 v[68:71], v[168:171], v[208:211], v[68:71]
	v_mfma_f32_16x16x32_bf16 v[120:123], v[148:151], v[180:183], v[120:123]
	v_mfma_f32_16x16x32_bf16 v[120:123], v[152:155], v[184:187], v[120:123]
	v_mfma_f32_16x16x32_bf16 v[104:107], v[148:151], v[188:191], v[104:107]
	v_mfma_f32_16x16x32_bf16 v[104:107], v[152:155], v[192:195], v[104:107]
	v_mfma_f32_16x16x32_bf16 v[88:91], v[148:151], v[196:199], v[88:91]
	v_mfma_f32_16x16x32_bf16 v[88:91], v[152:155], v[200:203], v[88:91]
	v_mfma_f32_16x16x32_bf16 v[72:75], v[148:151], v[204:207], v[72:75]
	v_mfma_f32_16x16x32_bf16 v[72:75], v[152:155], v[208:211], v[72:75]
	v_mfma_f32_16x16x32_bf16 v[112:115], v[172:175], v[180:183], v[112:115]
	v_mfma_f32_16x16x32_bf16 v[112:115], v[176:179], v[184:187], v[112:115]
	v_mfma_f32_16x16x32_bf16 v[96:99], v[172:175], v[188:191], v[96:99]
	v_mfma_f32_16x16x32_bf16 v[96:99], v[176:179], v[192:195], v[96:99]
	v_mfma_f32_16x16x32_bf16 v[80:83], v[172:175], v[196:199], v[80:83]
	v_mfma_f32_16x16x32_bf16 v[80:83], v[176:179], v[200:203], v[80:83]
	v_mfma_f32_16x16x32_bf16 v[64:67], v[172:175], v[204:207], v[64:67]
	v_mfma_f32_16x16x32_bf16 v[64:67], v[176:179], v[208:211], v[64:67]
	s_barrier
	s_add_i32 s30, s56, s38
	v_lshl_add_u64 v[160:161], v[160:161], 0, s[10:11]
	s_mov_b32 m0, s30
	ds_read_b128 v[180:183], v167 offset:49152
	ds_read_b128 v[184:187], v167 offset:50176
	ds_read_b128 v[188:191], v167 offset:51200
	ds_read_b128 v[192:195], v167 offset:52224
	ds_read_b128 v[196:199], v167 offset:53248
	ds_read_b128 v[200:203], v167 offset:54272
	ds_read_b128 v[204:207], v167 offset:55296
	ds_read_b128 v[208:211], v167 offset:56320
	global_load_lds_dwordx4 v[160:161], off
	s_add_i32 m0, s30, 0x2000
	s_add_u32 s28, s28, 0x200080
	v_lshl_add_u64 v[160:161], v[212:213], 0, s[10:11]
	s_addc_u32 s29, s29, 0
	s_add_i32 s30, s57, s38
	global_load_lds_dwordx4 v[160:161], off
	v_lshl_add_u64 v[160:161], s[28:29], 0, v[128:129]
	s_mov_b32 m0, s30
	s_nop 0
	global_load_lds_dwordx4 v[160:161], off
	v_lshl_add_u64 v[160:161], s[28:29], 0, v[130:131]
	s_add_i32 m0, s30, 0x2000
	s_nop 0
	global_load_lds_dwordx4 v[160:161], off
	v_lshl_add_u64 v[160:161], v[214:215], 0, s[10:11]
	s_mov_b32 m0, s45
	s_nop 0
	global_load_lds_dwordx4 v[160:161], off
	v_lshl_add_u64 v[160:161], v[216:217], 0, s[10:11]
	s_mov_b32 m0, s46
	s_nop 0
	global_load_lds_dwordx4 v[160:161], off
	s_waitcnt vmcnt(8)
	s_waitcnt lgkmcnt(0)
	s_barrier
	s_waitcnt lgkmcnt(0)
	v_mfma_f32_16x16x32_bf16 v[60:63], v[140:143], v[180:183], v[60:63]
	v_mfma_f32_16x16x32_bf16 v[60:63], v[144:147], v[184:187], v[60:63]
	v_mfma_f32_16x16x32_bf16 v[44:47], v[140:143], v[188:191], v[44:47]
	v_mfma_f32_16x16x32_bf16 v[44:47], v[144:147], v[192:195], v[44:47]
	v_mfma_f32_16x16x32_bf16 v[28:31], v[140:143], v[196:199], v[28:31]
	v_mfma_f32_16x16x32_bf16 v[28:31], v[144:147], v[200:203], v[28:31]
	v_mfma_f32_16x16x32_bf16 v[16:19], v[140:143], v[204:207], v[16:19]
	v_mfma_f32_16x16x32_bf16 v[16:19], v[144:147], v[208:211], v[16:19]
	v_mfma_f32_16x16x32_bf16 v[52:55], v[156:159], v[180:183], v[52:55]
	v_mfma_f32_16x16x32_bf16 v[52:55], v[168:171], v[184:187], v[52:55]
	v_mfma_f32_16x16x32_bf16 v[36:39], v[156:159], v[188:191], v[36:39]
	v_mfma_f32_16x16x32_bf16 v[36:39], v[168:171], v[192:195], v[36:39]
	v_mfma_f32_16x16x32_bf16 v[20:23], v[156:159], v[196:199], v[20:23]
	v_mfma_f32_16x16x32_bf16 v[20:23], v[168:171], v[200:203], v[20:23]
	v_mfma_f32_16x16x32_bf16 v[4:7], v[156:159], v[204:207], v[4:7]
	v_mfma_f32_16x16x32_bf16 v[4:7], v[168:171], v[208:211], v[4:7]
	v_mfma_f32_16x16x32_bf16 v[56:59], v[148:151], v[180:183], v[56:59]
	v_mfma_f32_16x16x32_bf16 v[56:59], v[152:155], v[184:187], v[56:59]
	v_mfma_f32_16x16x32_bf16 v[40:43], v[148:151], v[188:191], v[40:43]
	v_mfma_f32_16x16x32_bf16 v[40:43], v[152:155], v[192:195], v[40:43]
	v_mfma_f32_16x16x32_bf16 v[24:27], v[148:151], v[196:199], v[24:27]
	v_mfma_f32_16x16x32_bf16 v[24:27], v[152:155], v[200:203], v[24:27]
	v_mfma_f32_16x16x32_bf16 v[8:11], v[148:151], v[204:207], v[8:11]
	v_mfma_f32_16x16x32_bf16 v[8:11], v[152:155], v[208:211], v[8:11]
	v_mfma_f32_16x16x32_bf16 v[48:51], v[172:175], v[180:183], v[48:51]
	v_mfma_f32_16x16x32_bf16 v[48:51], v[176:179], v[184:187], v[48:51]
	v_mfma_f32_16x16x32_bf16 v[32:35], v[172:175], v[188:191], v[32:35]
	v_mfma_f32_16x16x32_bf16 v[32:35], v[176:179], v[192:195], v[32:35]
	v_mfma_f32_16x16x32_bf16 v[12:15], v[172:175], v[196:199], v[12:15]
	v_mfma_f32_16x16x32_bf16 v[12:15], v[176:179], v[200:203], v[12:15]
	v_mfma_f32_16x16x32_bf16 v[0:3], v[172:175], v[204:207], v[0:3]
	v_mfma_f32_16x16x32_bf16 v[0:3], v[176:179], v[208:211], v[0:3]
	s_barrier
	s_add_i32 s55, s55, 2
	s_add_u32 s26, s26, 0x100
	s_addc_u32 s27, s27, 0
	s_add_u32 s53, s53, 0x100
	s_addc_u32 s54, s54, 0
	s_cmpk_gt_u32 s55, 0x7d
	s_cbranch_scc0 .LBB0_1098
	s_and_b64 vcc, exec, s[14:15]
	s_cbranch_vccz .LBB0_1101
	s_barrier
